# v77 + GEMM: first two DMA waits of each unit's peeled K iteration relaxed (they only drained the previous epilogue's stores), prologue wait tightened so the first unit is covered
# baseline (speedup 1.0000x reference)
; #define PG8_STAGE(bufoff, gbase, voff) do { _Pragma("unroll") for (int _i = 0; _i < 2; ++_i) \
;         __builtin_amdgcn_global_load_lds((const unsigned*)((const char*)(gbase) + (voff)[_i]), (PG8_LAS unsigned*)(lds + (bufoff) + ldsw + _i * 8192), 16, 0, 0); } while (0)
; #define PG8_WAIT_V(n) asm volatile("s_waitcnt vmcnt(" #n ")" ::: "memory")
; #define PG8_BAR __builtin_amdgcn_s_barrier()
; template <class Epi, class Sched, bool ALIGN_EPI = false, bool SP2 = false>
; __device__ __forceinline__ void gemm_phase(PG8_LAS unsigned char* lds, const Gemm g, const Sched& S, const Epi& E) {
;     ...
;     const int tid = tid_o, wid = __builtin_amdgcn_readfirstlane(tid >> 6), lane = tid & 63, wr = wid >> 2, wc = wid & 3, fr = lane & 15, fq = lane >> 4;
;     const int K = g.K, nt = K / BK;
;     unsigned voffA[2], voffB[2];
; #pragma unroll
;     for (int i = 0; i < 2; ++i) { int R, C; stage_rc(tid * 16 + i * 8192, R, C); const int Rb = Epi::PERM ? ((R & ~31) + perm32(R & 31)) : R;
;         voffA[i] = (unsigned)(R * K + C) * 2u; voffB[i] = (unsigned)(Rb * K + C) * 2u; }
;     const size_t kstep = (size_t)(BK * 2);
;     const size_t hstep = (size_t)HALF * K * 2;
;     const size_t tstep = 2 * hstep;
;     const unsigned ldsw = (unsigned)wid * 1024u;
;     const int aoff = lds_byte(wr * 64 + fr, fq * 8), boff = lds_byte(wc * 32 + fr, fq * 8);
;     ...
;         PG8_STAGE(PG8_SB(0, 0), cB, voffB); PG8_STAGE(PG8_SB(0, 1), cB + hstep, voffB); PG8_STAGE(PG8_SA(0, 0), cA, voffA); PG8_STAGE(PG8_SA(0, 1), cA + hstep, voffA);
;         if (wr == 1) PG8_BAR;
;         PG8_WAIT_V(2); PG8_BAR;
;         PG8_STAGE(PG8_SB(1, 0), cB + kstep, voffB); PG8_STAGE(PG8_SA(1, 0), cA + kstep, voffA); PG8_STAGE(PG8_SB(1, 1), cB + hstep + kstep, voffB);
;         PG8_WAIT_V(6); PG8_BAR;
.LBB0_182:
	v_readlane_b32 s30, v254, 42
	v_mov_b32_e32 v155, v1
	v_readlane_b32 s31, v254, 43
	s_and_b32 s3, s3, 3
	s_add_i32 m0, s21, 0x18000
	v_lshl_add_u64 v[2:3], v[2:3], 0, s[0:1]
	v_lshl_add_u64 v[14:15], s[30:31], 0, v[154:155]
	v_mov_b32_e32 v159, v1
	s_lshl_b32 s14, s6, 13
	s_lshl_b32 s15, s3, 12
	s_waitcnt vmcnt(2)
	s_barrier
	global_load_lds_dwordx4 v[2:3], off
	v_lshl_add_u64 v[2:3], v[4:5], 0, s[0:1]
	s_add_i32 m0, s21, 0x1a000
	s_add_i32 s64, s21, 0x8000
	s_add_i32 s65, s21, 0xa000
	v_lshl_add_u64 v[16:17], s[30:31], 0, v[158:159]
	global_load_lds_dwordx4 v[2:3], off
	v_lshl_add_u64 v[2:3], v[14:15], 0, s[0:1]
	s_mov_b32 m0, s64
	s_add_u32 s8, s10, 0x40080
	global_load_lds_dwordx4 v[2:3], off
	v_lshl_add_u64 v[2:3], v[16:17], 0, s[0:1]
	s_mov_b32 m0, s65
	s_addc_u32 s9, s11, 0
	global_load_lds_dwordx4 v[2:3], off
	s_add_i32 m0, s21, 0x1c000
	v_lshl_add_u64 v[2:3], s[8:9], 0, v[156:157]
	global_load_lds_dwordx4 v[2:3], off
	v_lshl_add_u64 v[2:3], s[8:9], 0, v[160:161]
	s_add_i32 m0, s21, 0x1e000
	v_bfe_u32 v202, v6, 4, 2
	global_load_lds_dwordx4 v[2:3], off
	v_and_b32_e32 v2, 15, v6
	v_lshl_or_b32 v203, s6, 6, v2
	v_lshlrev_b32_e32 v3, 4, v202
	s_lshl_b32 s6, s6, 8
	s_add_i32 s8, 0, 0x22800
	v_lshl_or_b32 v3, v2, 6, v3
	v_lshlrev_b32_e32 v2, 2, v2
	s_add_i32 s6, s8, s6
	v_and_b32_e32 v4, 32, v2
	v_add_u32_e32 v205, s6, v2
	v_xor_b32_e32 v2, 16, v215
	s_cmpk_lt_u32 s2, 0x100
	v_cmp_lt_i32_e32 vcc, v2, v217
	s_cselect_b64 s[48:49], -1, 0
	s_lshl_b32 s66, s3, 6
	v_cndmask_b32_e32 v2, v215, v2, vcc
	v_readlane_b32 s2, v252, 53
	v_lshlrev_b32_e32 v207, 2, v2
	v_xor_b32_e32 v2, 32, v215
	v_readlane_b32 s3, v252, 54
	v_cmp_lt_i32_e32 vcc, v2, v217
	s_waitcnt vmcnt(0)
	v_bitop3_b32 v5, v3, s14, v4 bitop3:0xde
	v_lshl_add_u64 v[164:165], s[2:3], 0, v[0:1]
	v_lshlrev_b32_e32 v0, 14, v7
	v_cndmask_b32_e32 v2, v215, v2, vcc
	v_and_b32_e32 v0, 0xffff8000, v0
	v_lshlrev_b32_e32 v208, 2, v2
	v_lshl_add_u32 v0, v8, 11, v0
	v_and_b32_e32 v2, 1, v7
	v_lshl_or_b32 v0, v2, 6, v0
	v_lshl_add_u32 v166, v9, 1, v0
	v_lshlrev_b32_e32 v0, 14, v10
	v_and_b32_e32 v0, 0xffff8000, v0
	v_lshl_add_u32 v0, v11, 11, v0
	v_and_b32_e32 v2, 1, v10
	v_readlane_b32 s2, v254, 39
	v_lshl_or_b32 v0, v2, 6, v0
	v_readlane_b32 s3, v254, 40
	v_lshlrev_b32_e32 v162, 3, v202
	v_bitop3_b32 v204, v3, s15, v4 bitop3:0xde
	v_lshl_add_u32 v206, v163, 2, s8
	v_or_b32_e32 v209, 16, v203
	v_or_b32_e32 v210, 32, v203
	v_or_b32_e32 v211, 48, v203
	v_add_u32_e32 v221, 0x80, v203
	v_add_u32_e32 v222, 0x90, v203
	v_add_u32_e32 v223, 0xa0, v203
	v_add_u32_e32 v224, 0xb0, v203
	v_mov_b32_e32 v167, v1
	v_lshl_add_u32 v168, v12, 1, v0
	v_mov_b32_e32 v169, v1
	s_mov_b32 s6, 0
	v_add_u32_e32 v225, 0, v5
	v_readlane_b32 s3, v254, 25
	s_mov_b64 s[8:9], s[30:31]
	s_barrier
	s_branch .LBB0_185

; #define PG8_STAGE(bufoff, gbase, voff) do { _Pragma("unroll") for (int _i = 0; _i < 2; ++_i) \
;         __builtin_amdgcn_global_load_lds((const unsigned*)((const char*)(gbase) + (voff)[_i]), (PG8_LAS unsigned*)(lds + (bufoff) + ldsw + _i * 8192), 16, 0, 0); } while (0)
; #define PG8_LDA(dst, b, h) do { _Pragma("unroll") for (int m = 0; m < 4; ++m) _Pragma("unroll") for (int k = 0; k < 2; ++k) dst[m][k] = *(const PG8_LAS bf16x8*)(lds + PG8_SA(b, h) + aoff + m * 2048 + k * 1024); } while (0)
; #define PG8_LDB(dst, b, h) do { _Pragma("unroll") for (int n = 0; n < 2; ++n) _Pragma("unroll") for (int k = 0; k < 2; ++k) dst[n][k] = *(const PG8_LAS bf16x8*)(lds + PG8_SB(b, h) + boff + n * 2048 + k * 1024); } while (0)
; #define PG8_MMA(ai, bj, At, Bt) do { __builtin_amdgcn_s_setprio(1); _Pragma("unroll") for (int m = 0; m < 4; ++m) _Pragma("unroll") for (int n = 0; n < 2; ++n) _Pragma("unroll") for (int k = 0; k < 2; ++k) \
;         acc[ai][bj][m][n] = __builtin_amdgcn_mfma_f32_16x16x32_bf16(Bt[n][k], At[m][k], acc[ai][bj][m][n], 0, 0, 0); __builtin_amdgcn_s_setprio(0); } while (0)
; #define PG8_WAIT_V(n) asm volatile("s_waitcnt vmcnt(" #n ")" ::: "memory")
; #define PG8_WAIT_L(n) asm volatile("s_waitcnt lgkmcnt(" #n ")" ::: "memory")
; #define PG8_BAR __builtin_amdgcn_s_barrier()
; #define PG8_SCHED __builtin_amdgcn_sched_barrier(0)
; template <class Epi, class Sched, bool ALIGN_EPI = false, bool SP2 = false>
; __device__ __forceinline__ void gemm_phase(PG8_LAS unsigned char* lds, const Gemm g, const Sched& S, const Epi& E) {
;     ...
;             PG8_LDB(B0, 0, 0); PG8_LDB(B1, 0, 1); PG8_SCHED; PG8_LDA(At, 0, 0); PG8_STAGE(PG8_SA(1, 1), a1 + hstep, voffA);
;             PG8_WAIT_V(8); PG8_WAIT_L(0); PG8_BAR; PG8_MMA(0, 0, At, B0); PG8_MMA(0, 1, At, B1); PG8_BAR; PG8_SCHED;
;             PG8_LDA(At, 0, 1); PG8_STAGE(PG8_SB(0, 0), b2, voffB); PG8_STAGE(PG8_SB(0, 1), b2 + hstep, voffB); PG8_STAGE(PG8_SA(0, 0), a2, voffA);
;             PG8_WAIT_V(8); PG8_WAIT_L(0); PG8_BAR; PG8_MMA(1, 0, At, B0); PG8_MMA(1, 1, At, B1); PG8_BAR; PG8_SCHED;
.Lpeel_p1:
	s_add_u32 s10, s8, 0xfffc0080
	s_addc_u32 s11, s9, -1
	s_add_i32 s30, 0, 0x10000
	s_cmp_eq_u32 s43, 12
	s_cselect_b32 s15, s33, s11
	s_cselect_b32 s14, s34, s10
	v_add_u32_e32 v0, s30, v204
	s_cselect_b32 s11, s35, s42
	s_cselect_b32 s10, s40, s41
	s_add_i32 s51, 0, 0x14000
	ds_read_b128 v[18:21], v0
	ds_read_b128 v[22:25], v0 offset:1024
	ds_read_b128 v[26:29], v0 offset:2048
	ds_read_b128 v[30:33], v0 offset:3072
	v_add_u32_e32 v0, s51, v204
	ds_read_b128 v[46:49], v0
	ds_read_b128 v[54:57], v0 offset:1024
	ds_read_b128 v[170:173], v0 offset:2048
	ds_read_b128 v[174:177], v0 offset:3072
	v_lshl_add_u64 v[190:191], s[8:9], 0, v[166:167]
	s_add_i32 m0, s21, 0xc000
	ds_read_b128 v[178:181], v225
	ds_read_b128 v[182:185], v225 offset:1024
	ds_read_b128 v[186:189], v225 offset:2048
	ds_read_b128 v[226:229], v225 offset:3072
	ds_read_b128 v[230:233], v225 offset:4096
	ds_read_b128 v[234:237], v225 offset:5120
	ds_read_b128 v[238:241], v225 offset:6144
	ds_read_b128 v[242:245], v225 offset:7168
	global_load_lds_dwordx4 v[190:191], off
	v_lshl_add_u64 v[190:191], s[8:9], 0, v[168:169]
	s_add_i32 m0, s21, 0xe000
	s_nop 0
	global_load_lds_dwordx4 v[190:191], off
	s_waitcnt vmcnt(63)
	s_waitcnt lgkmcnt(0)
	s_barrier
	s_setprio 1
	s_waitcnt lgkmcnt(0)
	v_mfma_f32_16x16x32_bf16 v[150:153], v[18:21], v[178:181], 0
	v_mfma_f32_16x16x32_bf16 v[146:149], v[26:29], v[178:181], 0
	v_mfma_f32_16x16x32_bf16 v[134:137], v[18:21], v[186:189], 0
	v_mfma_f32_16x16x32_bf16 v[130:133], v[26:29], v[186:189], 0
	v_mfma_f32_16x16x32_bf16 v[118:121], v[18:21], v[230:233], 0
	v_mfma_f32_16x16x32_bf16 v[114:117], v[26:29], v[230:233], 0
	v_mfma_f32_16x16x32_bf16 v[102:105], v[18:21], v[238:241], 0
	v_mfma_f32_16x16x32_bf16 v[98:101], v[26:29], v[238:241], 0
	v_mfma_f32_16x16x32_bf16 v[150:153], v[22:25], v[182:185], v[150:153]
	v_mfma_f32_16x16x32_bf16 v[146:149], v[30:33], v[182:185], v[146:149]
	v_mfma_f32_16x16x32_bf16 v[134:137], v[22:25], v[226:229], v[134:137]
	v_mfma_f32_16x16x32_bf16 v[130:133], v[30:33], v[226:229], v[130:133]
	v_mfma_f32_16x16x32_bf16 v[118:121], v[22:25], v[234:237], v[118:121]
	v_mfma_f32_16x16x32_bf16 v[114:117], v[30:33], v[234:237], v[114:117]
	v_mfma_f32_16x16x32_bf16 v[102:105], v[22:25], v[242:245], v[102:105]
	v_mfma_f32_16x16x32_bf16 v[98:101], v[30:33], v[242:245], v[98:101]
	s_setprio 0
	s_setprio 1
	v_mfma_f32_16x16x32_bf16 v[142:145], v[46:49], v[178:181], 0
	v_mfma_f32_16x16x32_bf16 v[138:141], v[170:173], v[178:181], 0
	v_mfma_f32_16x16x32_bf16 v[126:129], v[46:49], v[186:189], 0
	v_mfma_f32_16x16x32_bf16 v[122:125], v[170:173], v[186:189], 0
	v_mfma_f32_16x16x32_bf16 v[110:113], v[46:49], v[230:233], 0
	v_mfma_f32_16x16x32_bf16 v[106:109], v[170:173], v[230:233], 0
	v_mfma_f32_16x16x32_bf16 v[94:97], v[46:49], v[238:241], 0
	v_mfma_f32_16x16x32_bf16 v[90:93], v[170:173], v[238:241], 0
	v_mfma_f32_16x16x32_bf16 v[142:145], v[54:57], v[182:185], v[142:145]
	v_mfma_f32_16x16x32_bf16 v[138:141], v[174:177], v[182:185], v[138:141]
	v_mfma_f32_16x16x32_bf16 v[126:129], v[54:57], v[226:229], v[126:129]
	v_mfma_f32_16x16x32_bf16 v[122:125], v[174:177], v[226:229], v[122:125]
	v_mfma_f32_16x16x32_bf16 v[110:113], v[54:57], v[234:237], v[110:113]
	v_mfma_f32_16x16x32_bf16 v[106:109], v[174:177], v[234:237], v[106:109]
	v_mfma_f32_16x16x32_bf16 v[94:97], v[54:57], v[242:245], v[94:97]
	v_mfma_f32_16x16x32_bf16 v[90:93], v[174:177], v[242:245], v[90:93]
	s_setprio 0
	s_barrier
	s_add_i32 s30, s30, s20
	v_lshl_add_u64 v[190:191], s[10:11], 0, v[156:157]
	s_mov_b32 m0, s30
	ds_read_b128 v[178:181], v225 offset:16384
	ds_read_b128 v[182:185], v225 offset:17408
	ds_read_b128 v[186:189], v225 offset:18432
	ds_read_b128 v[226:229], v225 offset:19456
	ds_read_b128 v[230:233], v225 offset:20480
	ds_read_b128 v[234:237], v225 offset:21504
	ds_read_b128 v[238:241], v225 offset:22528
	ds_read_b128 v[242:245], v225 offset:23552
	global_load_lds_dwordx4 v[190:191], off
	s_add_i32 m0, s30, 0x2000
	s_add_u32 s30, s10, 0x40000
	v_lshl_add_u64 v[198:199], s[10:11], 0, v[160:161]
	s_addc_u32 s31, s11, 0
	s_add_i32 s51, s51, s20
	global_load_lds_dwordx4 v[198:199], off
	v_lshl_add_u64 v[200:201], s[30:31], 0, v[156:157]
	s_mov_b32 m0, s51
	v_lshl_add_u64 v[250:251], s[14:15], 0, v[158:159]
	global_load_lds_dwordx4 v[200:201], off
	v_lshl_add_u64 v[200:201], s[30:31], 0, v[160:161]
	s_add_i32 m0, s51, 0x2000
	s_nop 0
	global_load_lds_dwordx4 v[200:201], off
	v_lshl_add_u64 v[200:201], s[14:15], 0, v[154:155]
	s_mov_b32 m0, s21
	s_nop 0
	global_load_lds_dwordx4 v[200:201], off
	s_mov_b32 m0, s45
	s_nop 0
	global_load_lds_dwordx4 v[250:251], off
	s_waitcnt vmcnt(63)
	s_waitcnt lgkmcnt(0)
	s_barrier
; #define PG8_STAGE(bufoff, gbase, voff) do { _Pragma("unroll") for (int _i = 0; _i < 2; ++_i) \
;         __builtin_amdgcn_global_load_lds((const unsigned*)((const char*)(gbase) + (voff)[_i]), (PG8_LAS unsigned*)(lds + (bufoff) + ldsw + _i * 8192), 16, 0, 0); } while (0)
; #define PG8_LDA(dst, b, h) do { _Pragma("unroll") for (int m = 0; m < 4; ++m) _Pragma("unroll") for (int k = 0; k < 2; ++k) dst[m][k] = *(const PG8_LAS bf16x8*)(lds + PG8_SA(b, h) + aoff + m * 2048 + k * 1024); } while (0)
; #define PG8_LDB(dst, b, h) do { _Pragma("unroll") for (int n = 0; n < 2; ++n) _Pragma("unroll") for (int k = 0; k < 2; ++k) dst[n][k] = *(const PG8_LAS bf16x8*)(lds + PG8_SB(b, h) + boff + n * 2048 + k * 1024); } while (0)
; #define PG8_MMA(ai, bj, At, Bt) do { __builtin_amdgcn_s_setprio(1); _Pragma("unroll") for (int m = 0; m < 4; ++m) _Pragma("unroll") for (int n = 0; n < 2; ++n) _Pragma("unroll") for (int k = 0; k < 2; ++k) \
;         acc[ai][bj][m][n] = __builtin_amdgcn_mfma_f32_16x16x32_bf16(Bt[n][k], At[m][k], acc[ai][bj][m][n], 0, 0, 0); __builtin_amdgcn_s_setprio(0); } while (0)
; #define PG8_WAIT_V(n) asm volatile("s_waitcnt vmcnt(" #n ")" ::: "memory")
; #define PG8_WAIT_L(n) asm volatile("s_waitcnt lgkmcnt(" #n ")" ::: "memory")
; #define PG8_BAR __builtin_amdgcn_s_barrier()
; #define PG8_SCHED __builtin_amdgcn_sched_barrier(0)
; template <class Epi, class Sched, bool ALIGN_EPI = false, bool SP2 = false>
; __device__ __forceinline__ void gemm_phase(PG8_LAS unsigned char* lds, const Gemm g, const Sched& S, const Epi& E) {
;     ...
;             PG8_WAIT_V(8); PG8_WAIT_L(0); PG8_BAR; PG8_MMA(1, 0, At, B0); PG8_MMA(1, 1, At, B1); PG8_BAR; PG8_SCHED;
;             PG8_LDB(B0, 1, 0); PG8_LDB(B1, 1, 1); PG8_SCHED; PG8_LDA(At, 1, 0); PG8_STAGE(PG8_SA(0, 1), a2 + hstep, voffA);
;             PG8_WAIT_V(8); PG8_WAIT_L(0); PG8_BAR; PG8_MMA(0, 0, At, B0); PG8_MMA(0, 1, At, B1); PG8_BAR; PG8_SCHED;
	s_setprio 1
	s_waitcnt lgkmcnt(0)
	v_mfma_f32_16x16x32_bf16 v[86:89], v[18:21], v[178:181], 0
	v_mfma_f32_16x16x32_bf16 v[82:85], v[26:29], v[178:181], 0
	v_mfma_f32_16x16x32_bf16 v[70:73], v[18:21], v[186:189], 0
	v_mfma_f32_16x16x32_bf16 v[66:69], v[26:29], v[186:189], 0
	v_mfma_f32_16x16x32_bf16 v[50:53], v[18:21], v[230:233], 0
	v_mfma_f32_16x16x32_bf16 v[42:45], v[26:29], v[230:233], 0
	v_mfma_f32_16x16x32_bf16 v[14:17], v[18:21], v[238:241], 0
	v_mfma_f32_16x16x32_bf16 v[10:13], v[26:29], v[238:241], 0
	v_mfma_f32_16x16x32_bf16 v[86:89], v[22:25], v[182:185], v[86:89]
	v_mfma_f32_16x16x32_bf16 v[82:85], v[30:33], v[182:185], v[82:85]
	v_mfma_f32_16x16x32_bf16 v[70:73], v[22:25], v[226:229], v[70:73]
	v_mfma_f32_16x16x32_bf16 v[66:69], v[30:33], v[226:229], v[66:69]
	v_mfma_f32_16x16x32_bf16 v[50:53], v[22:25], v[234:237], v[50:53]
	v_mfma_f32_16x16x32_bf16 v[42:45], v[30:33], v[234:237], v[42:45]
	v_mfma_f32_16x16x32_bf16 v[14:17], v[22:25], v[242:245], v[14:17]
	v_mfma_f32_16x16x32_bf16 v[10:13], v[30:33], v[242:245], v[10:13]
	s_setprio 0
	s_setprio 1
	v_mfma_f32_16x16x32_bf16 v[38:41], v[46:49], v[230:233], 0
	v_mfma_f32_16x16x32_bf16 v[34:37], v[170:173], v[230:233], 0
	v_mfma_f32_16x16x32_bf16 v[6:9], v[46:49], v[238:241], 0
	v_mfma_f32_16x16x32_bf16 v[2:5], v[170:173], v[238:241], 0
	v_mfma_f32_16x16x32_bf16 v[18:21], v[46:49], v[178:181], 0
	v_mfma_f32_16x16x32_bf16 v[22:25], v[170:173], v[178:181], 0
	v_mfma_f32_16x16x32_bf16 v[26:29], v[46:49], v[186:189], 0
	v_mfma_f32_16x16x32_bf16 v[30:33], v[170:173], v[186:189], 0
	v_mfma_f32_16x16x32_bf16 v[38:41], v[54:57], v[234:237], v[38:41]
	v_mfma_f32_16x16x32_bf16 v[34:37], v[174:177], v[234:237], v[34:37]
	v_mfma_f32_16x16x32_bf16 v[6:9], v[54:57], v[242:245], v[6:9]
	v_mfma_f32_16x16x32_bf16 v[2:5], v[174:177], v[242:245], v[2:5]
	v_mfma_f32_16x16x32_bf16 v[18:21], v[54:57], v[182:185], v[18:21]
	v_mfma_f32_16x16x32_bf16 v[22:25], v[174:177], v[182:185], v[22:25]
	v_mfma_f32_16x16x32_bf16 v[26:29], v[54:57], v[226:229], v[26:29]
	v_mfma_f32_16x16x32_bf16 v[30:33], v[174:177], v[226:229], v[30:33]
	s_setprio 0
	s_barrier
	s_add_i32 s30, 0, 0x18000
	v_add_u32_e32 v0, s30, v204
	s_add_i32 s31, 0, 0x1c000
	ds_read_b128 v[46:49], v0
	ds_read_b128 v[54:57], v0 offset:1024
	ds_read_b128 v[58:61], v0 offset:2048
	ds_read_b128 v[62:65], v0 offset:3072
	v_add_u32_e32 v0, s31, v204
	ds_read_b128 v[170:173], v0
	ds_read_b128 v[174:177], v0 offset:1024
	ds_read_b128 v[178:181], v0 offset:2048
	ds_read_b128 v[182:185], v0 offset:3072
	s_add_u32 s14, s14, 0x40000
	s_addc_u32 s15, s15, 0
	s_mov_b32 m0, s62
	v_lshl_add_u64 v[246:247], s[14:15], 0, v[154:155]
	ds_read_b128 v[74:77], v225 offset:32768
	ds_read_b128 v[78:81], v225 offset:33792
	ds_read_b128 v[186:189], v225 offset:34816
	ds_read_b128 v[226:229], v225 offset:35840
	ds_read_b128 v[230:233], v225 offset:36864
	ds_read_b128 v[234:237], v225 offset:37888
	ds_read_b128 v[238:241], v225 offset:38912
	ds_read_b128 v[242:245], v225 offset:39936
	global_load_lds_dwordx4 v[246:247], off
	v_lshl_add_u64 v[246:247], s[14:15], 0, v[158:159]
	s_mov_b32 m0, s63
	s_nop 0
	global_load_lds_dwordx4 v[246:247], off
	s_waitcnt vmcnt(8)
	s_waitcnt lgkmcnt(0)
	s_barrier
	s_setprio 1
	s_waitcnt lgkmcnt(0)
	v_mfma_f32_16x16x32_bf16 v[150:153], v[46:49], v[74:77], v[150:153]
	v_mfma_f32_16x16x32_bf16 v[146:149], v[58:61], v[74:77], v[146:149]
	v_mfma_f32_16x16x32_bf16 v[134:137], v[46:49], v[186:189], v[134:137]
	v_mfma_f32_16x16x32_bf16 v[130:133], v[58:61], v[186:189], v[130:133]
	v_mfma_f32_16x16x32_bf16 v[118:121], v[46:49], v[230:233], v[118:121]
	v_mfma_f32_16x16x32_bf16 v[114:117], v[58:61], v[230:233], v[114:117]
	v_mfma_f32_16x16x32_bf16 v[102:105], v[46:49], v[238:241], v[102:105]
	v_mfma_f32_16x16x32_bf16 v[98:101], v[58:61], v[238:241], v[98:101]
	v_mfma_f32_16x16x32_bf16 v[150:153], v[54:57], v[78:81], v[150:153]
	v_mfma_f32_16x16x32_bf16 v[146:149], v[62:65], v[78:81], v[146:149]
	v_mfma_f32_16x16x32_bf16 v[134:137], v[54:57], v[226:229], v[134:137]
	v_mfma_f32_16x16x32_bf16 v[130:133], v[62:65], v[226:229], v[130:133]
	v_mfma_f32_16x16x32_bf16 v[118:121], v[54:57], v[234:237], v[118:121]
	v_mfma_f32_16x16x32_bf16 v[114:117], v[62:65], v[234:237], v[114:117]
	v_mfma_f32_16x16x32_bf16 v[102:105], v[54:57], v[242:245], v[102:105]
	v_mfma_f32_16x16x32_bf16 v[98:101], v[62:65], v[242:245], v[98:101]
	s_setprio 0
	s_setprio 1
	v_mfma_f32_16x16x32_bf16 v[142:145], v[170:173], v[74:77], v[142:145]
	v_mfma_f32_16x16x32_bf16 v[74:77], v[178:181], v[74:77], v[138:141]
	v_mfma_f32_16x16x32_bf16 v[138:141], v[182:185], v[78:81], v[74:77]
	v_mfma_f32_16x16x32_bf16 v[74:77], v[170:173], v[186:189], v[126:129]
	v_mfma_f32_16x16x32_bf16 v[126:129], v[174:177], v[226:229], v[74:77]
	v_mfma_f32_16x16x32_bf16 v[74:77], v[178:181], v[186:189], v[122:125]
	v_mfma_f32_16x16x32_bf16 v[122:125], v[182:185], v[226:229], v[74:77]
	v_mfma_f32_16x16x32_bf16 v[74:77], v[170:173], v[230:233], v[110:113]
	v_mfma_f32_16x16x32_bf16 v[110:113], v[174:177], v[234:237], v[74:77]
	v_mfma_f32_16x16x32_bf16 v[74:77], v[178:181], v[230:233], v[106:109]
	v_mfma_f32_16x16x32_bf16 v[106:109], v[182:185], v[234:237], v[74:77]
	v_mfma_f32_16x16x32_bf16 v[74:77], v[170:173], v[238:241], v[94:97]
	v_mfma_f32_16x16x32_bf16 v[94:97], v[174:177], v[242:245], v[74:77]
	v_mfma_f32_16x16x32_bf16 v[74:77], v[178:181], v[238:241], v[90:93]
	v_mfma_f32_16x16x32_bf16 v[142:145], v[174:177], v[78:81], v[142:145]
	v_mfma_f32_16x16x32_bf16 v[90:93], v[182:185], v[242:245], v[74:77]
	s_setprio 0
	s_barrier
; #define PG8_STAGE(bufoff, gbase, voff) do { _Pragma("unroll") for (int _i = 0; _i < 2; ++_i) \
;         __builtin_amdgcn_global_load_lds((const unsigned*)((const char*)(gbase) + (voff)[_i]), (PG8_LAS unsigned*)(lds + (bufoff) + ldsw + _i * 8192), 16, 0, 0); } while (0)
; #define PG8_LDA(dst, b, h) do { _Pragma("unroll") for (int m = 0; m < 4; ++m) _Pragma("unroll") for (int k = 0; k < 2; ++k) dst[m][k] = *(const PG8_LAS bf16x8*)(lds + PG8_SA(b, h) + aoff + m * 2048 + k * 1024); } while (0)
; #define PG8_MMA(ai, bj, At, Bt) do { __builtin_amdgcn_s_setprio(1); _Pragma("unroll") for (int m = 0; m < 4; ++m) _Pragma("unroll") for (int n = 0; n < 2; ++n) _Pragma("unroll") for (int k = 0; k < 2; ++k) \
;         acc[ai][bj][m][n] = __builtin_amdgcn_mfma_f32_16x16x32_bf16(Bt[n][k], At[m][k], acc[ai][bj][m][n], 0, 0, 0); __builtin_amdgcn_s_setprio(0); } while (0)
; #define PG8_WAIT_V(n) asm volatile("s_waitcnt vmcnt(" #n ")" ::: "memory")
; #define PG8_WAIT_L(n) asm volatile("s_waitcnt lgkmcnt(" #n ")" ::: "memory")
; #define PG8_BAR __builtin_amdgcn_s_barrier()
; #define PG8_SCHED __builtin_amdgcn_sched_barrier(0)
; template <class Epi, class Sched, bool ALIGN_EPI = false, bool SP2 = false>
; __device__ __forceinline__ void gemm_phase(PG8_LAS unsigned char* lds, const Gemm g, const Sched& S, const Epi& E) {
;     ...
;         for (int t = 0; t < nt; t += 2) {
;             const bool last = (t == nt - 2);
;             const char* a1 = cA + (size_t)(t + 1) * kstep;
;             const char* a2 = last ? nA : cA + (size_t)(t + 2) * kstep; const char* b2 = last ? nB : cB + (size_t)(t + 2) * kstep;
;     ...
;             PG8_LDA(At, 1, 1); PG8_STAGE(PG8_SB(1, 0), b3, voffB); PG8_STAGE(PG8_SB(1, 1), b3 + hstep, voffB); PG8_STAGE(PG8_SA(1, 0), a3, voffA);
;             PG8_WAIT_V(8); PG8_WAIT_L(0); PG8_BAR; PG8_MMA(1, 0, At, B0); PG8_MMA(1, 1, At, B1); PG8_BAR; PG8_SCHED;
	s_add_i32 s14, s30, s20
	v_lshl_add_u64 v[78:79], v[190:191], 0, s[0:1]
	s_mov_b32 m0, s14
	s_nop 0
	ds_read_b128 v[74:77], v225 offset:49152
	ds_read_b128 v[186:189], v225 offset:50176
	ds_read_b128 v[226:229], v225 offset:51200
	ds_read_b128 v[230:233], v225 offset:52224
	ds_read_b128 v[234:237], v225 offset:53248
	ds_read_b128 v[238:241], v225 offset:54272
	ds_read_b128 v[242:245], v225 offset:55296
	ds_read_b128 v[246:249], v225 offset:56320
	global_load_lds_dwordx4 v[78:79], off
	s_add_i32 m0, s14, 0x2000
	s_add_u32 s10, s10, 0x40080
	v_lshl_add_u64 v[78:79], v[198:199], 0, s[0:1]
	s_addc_u32 s11, s11, 0
	s_add_i32 s14, s31, s20
	global_load_lds_dwordx4 v[78:79], off
	v_lshl_add_u64 v[78:79], s[10:11], 0, v[156:157]
	s_mov_b32 m0, s14
	s_nop 0
	global_load_lds_dwordx4 v[78:79], off
	v_lshl_add_u64 v[78:79], s[10:11], 0, v[160:161]
	s_add_i32 m0, s14, 0x2000
	s_nop 0
	global_load_lds_dwordx4 v[78:79], off
	v_lshl_add_u64 v[78:79], v[200:201], 0, s[0:1]
	s_mov_b32 m0, s64
	s_nop 0
	global_load_lds_dwordx4 v[78:79], off
	v_lshl_add_u64 v[78:79], v[250:251], 0, s[0:1]
	s_mov_b32 m0, s65
	s_nop 0
	global_load_lds_dwordx4 v[78:79], off
	s_waitcnt vmcnt(8)
	s_waitcnt lgkmcnt(0)
	s_barrier
	s_setprio 1
	s_waitcnt lgkmcnt(0)
	v_mfma_f32_16x16x32_bf16 v[78:81], v[46:49], v[74:77], v[86:89]
	v_mfma_f32_16x16x32_bf16 v[86:89], v[54:57], v[186:189], v[78:81]
	v_mfma_f32_16x16x32_bf16 v[78:81], v[58:61], v[74:77], v[82:85]
	v_mfma_f32_16x16x32_bf16 v[70:73], v[46:49], v[226:229], v[70:73]
	v_mfma_f32_16x16x32_bf16 v[66:69], v[58:61], v[226:229], v[66:69]
	v_mfma_f32_16x16x32_bf16 v[50:53], v[46:49], v[234:237], v[50:53]
	v_mfma_f32_16x16x32_bf16 v[42:45], v[58:61], v[234:237], v[42:45]
	v_mfma_f32_16x16x32_bf16 v[14:17], v[46:49], v[242:245], v[14:17]
	v_mfma_f32_16x16x32_bf16 v[10:13], v[58:61], v[242:245], v[10:13]
	v_mfma_f32_16x16x32_bf16 v[82:85], v[62:65], v[186:189], v[78:81]
	v_mfma_f32_16x16x32_bf16 v[70:73], v[54:57], v[230:233], v[70:73]
	v_mfma_f32_16x16x32_bf16 v[66:69], v[62:65], v[230:233], v[66:69]
	v_mfma_f32_16x16x32_bf16 v[50:53], v[54:57], v[238:241], v[50:53]
	v_mfma_f32_16x16x32_bf16 v[42:45], v[62:65], v[238:241], v[42:45]
	v_mfma_f32_16x16x32_bf16 v[14:17], v[54:57], v[246:249], v[14:17]
	v_mfma_f32_16x16x32_bf16 v[10:13], v[62:65], v[246:249], v[10:13]
	s_setprio 0
	s_setprio 1
	v_mfma_f32_16x16x32_bf16 v[18:21], v[170:173], v[74:77], v[18:21]
	v_mfma_f32_16x16x32_bf16 v[78:81], v[174:177], v[186:189], v[18:21]
	v_mfma_f32_16x16x32_bf16 v[18:21], v[178:181], v[74:77], v[22:25]
	v_mfma_f32_16x16x32_bf16 v[74:77], v[182:185], v[186:189], v[18:21]
	v_mfma_f32_16x16x32_bf16 v[18:21], v[170:173], v[226:229], v[26:29]
	v_mfma_f32_16x16x32_bf16 v[62:65], v[174:177], v[230:233], v[18:21]
	v_mfma_f32_16x16x32_bf16 v[18:21], v[178:181], v[226:229], v[30:33]
	v_mfma_f32_16x16x32_bf16 v[58:61], v[182:185], v[230:233], v[18:21]
	v_mfma_f32_16x16x32_bf16 v[18:21], v[170:173], v[234:237], v[38:41]
	v_mfma_f32_16x16x32_bf16 v[38:41], v[174:177], v[238:241], v[18:21]
	v_mfma_f32_16x16x32_bf16 v[18:21], v[178:181], v[234:237], v[34:37]
	v_mfma_f32_16x16x32_bf16 v[6:9], v[170:173], v[242:245], v[6:9]
	v_mfma_f32_16x16x32_bf16 v[2:5], v[178:181], v[242:245], v[2:5]
	v_mfma_f32_16x16x32_bf16 v[34:37], v[182:185], v[238:241], v[18:21]
	v_mfma_f32_16x16x32_bf16 v[6:9], v[174:177], v[246:249], v[6:9]
	v_mfma_f32_16x16x32_bf16 v[2:5], v[182:185], v[246:249], v[2:5]
	s_setprio 0
	s_barrier
	s_add_i32 s43, s43, 2
	s_add_u32 s8, s8, 0x100
	s_addc_u32 s9, s9, 0
	s_add_u32 s41, s41, 0x100
	s_addc_u32 s42, s42, 0
	s_cmp_gt_u32 s43, 13
	s_cbranch_scc0 .LBB0_188
	s_branch .Lpeel_exit_p1

; #define PG8_STAGE(bufoff, gbase, voff) do { _Pragma("unroll") for (int _i = 0; _i < 2; ++_i) \
;         __builtin_amdgcn_global_load_lds((const unsigned*)((const char*)(gbase) + (voff)[_i]), (PG8_LAS unsigned*)(lds + (bufoff) + ldsw + _i * 8192), 16, 0, 0); } while (0)
; #define PG8_WAIT_V(n) asm volatile("s_waitcnt vmcnt(" #n ")" ::: "memory")
; #define PG8_BAR __builtin_amdgcn_s_barrier()
; template <class Epi, class Sched, bool ALIGN_EPI = false, bool SP2 = false>
; __device__ __forceinline__ void gemm_phase(PG8_LAS unsigned char* lds, const Gemm g, const Sched& S, const Epi& E) {
;     ...
;     for (int i = 0; i < 2; ++i) { int R, C; stage_rc(tid * 16 + i * 8192, R, C); const int Rb = Epi::PERM ? ((R & ~31) + perm32(R & 31)) : R;
;         voffA[i] = (unsigned)(R * K + C) * 2u; voffB[i] = (unsigned)(Rb * K + C) * 2u; }
;     const size_t kstep = (size_t)(BK * 2);
;     const size_t hstep = (size_t)HALF * K * 2;
;     const size_t tstep = 2 * hstep;
;     const unsigned ldsw = (unsigned)wid * 1024u;
;     const int aoff = lds_byte(wr * 64 + fr, fq * 8), boff = lds_byte(wc * 32 + fr, fq * 8);
;     ...
;         PG8_STAGE(PG8_SB(0, 0), cB, voffB); PG8_STAGE(PG8_SB(0, 1), cB + hstep, voffB); PG8_STAGE(PG8_SA(0, 0), cA, voffA); PG8_STAGE(PG8_SA(0, 1), cA + hstep, voffA);
;         if (wr == 1) PG8_BAR;
;         PG8_WAIT_V(2); PG8_BAR;
;         PG8_STAGE(PG8_SB(1, 0), cB + kstep, voffB); PG8_STAGE(PG8_SA(1, 0), cA + kstep, voffA); PG8_STAGE(PG8_SB(1, 1), cB + hstep + kstep, voffB);
;         PG8_WAIT_V(6); PG8_BAR;
.LBB0_666:
	v_bfe_u32 v18, v8, 4, 2
	v_and_b32_e32 v184, 15, v8
	v_lshlrev_b32_e32 v9, 4, v18
	v_lshlrev_b32_e32 v8, 2, v8
	s_and_b32 s54, s9, 3
	s_lshl_b32 s55, s8, 6
	v_lshl_or_b32 v9, v184, 6, v9
	s_lshl_b32 s8, s8, 13
	v_and_b32_e32 v8, 32, v8
	v_lshl_add_u64 v[10:11], s[46:47], 0, v[0:1]
	v_mov_b32_e32 v155, v1
	v_readlane_b32 s44, v254, 48
	v_bitop3_b32 v20, v9, s8, v8 bitop3:0xde
	s_lshl_b32 s8, s54, 12
	v_lshl_add_u64 v[12:13], s[46:47], 0, v[154:155]
	v_mov_b32_e32 v159, v1
	v_readlane_b32 s45, v254, 49
	v_bitop3_b32 v185, v9, s8, v8 bitop3:0xde
	s_add_i32 m0, s50, 0x18000
	v_lshl_add_u64 v[8:9], v[10:11], 0, s[0:1]
	v_lshl_add_u64 v[14:15], s[44:45], 0, v[158:159]
	v_mov_b32_e32 v157, v1
	s_waitcnt vmcnt(2)
	s_barrier
	global_load_lds_dwordx4 v[8:9], off
	v_lshl_add_u64 v[8:9], v[12:13], 0, s[0:1]
	s_add_i32 m0, s50, 0x1a000
	s_add_i32 s56, s50, 0x8000
	s_add_i32 s57, s50, 0xa000
	v_lshl_add_u64 v[16:17], s[44:45], 0, v[156:157]
	global_load_lds_dwordx4 v[8:9], off
	v_lshl_add_u64 v[8:9], v[14:15], 0, s[0:1]
	s_mov_b32 m0, s56
	s_add_u32 s8, s46, 0x40080
	global_load_lds_dwordx4 v[8:9], off
	v_lshl_add_u64 v[8:9], v[16:17], 0, s[0:1]
	s_mov_b32 m0, s57
	s_addc_u32 s9, s47, 0
	global_load_lds_dwordx4 v[8:9], off
	s_add_i32 m0, s50, 0x1c000
	v_lshl_add_u64 v[8:9], s[8:9], 0, v[0:1]
	global_load_lds_dwordx4 v[8:9], off
	v_lshl_add_u64 v[8:9], s[8:9], 0, v[154:155]
	s_add_i32 m0, s50, 0x1e000
	v_lshlrev_b32_e32 v19, 3, v18
	global_load_lds_dwordx4 v[8:9], off
	v_lshlrev_b32_e32 v8, 14, v6
	v_and_b32_e32 v8, 0xffff8000, v8
	v_lshl_add_u32 v5, v5, 11, v8
	v_and_b32_e32 v6, 1, v6
	v_lshl_or_b32 v5, v6, 6, v5
	s_waitcnt vmcnt(0)
	v_lshl_add_u32 v160, v7, 1, v5
	v_lshlrev_b32_e32 v5, 14, v2
	v_and_b32_e32 v5, 0xffff8000, v5
	s_waitcnt vmcnt(0)
	v_lshl_add_u32 v3, v3, 11, v5
	v_and_b32_e32 v2, 1, v2
	s_cmpk_lt_u32 s6, 0x100
	v_lshl_or_b32 v2, v2, 6, v3
	v_readlane_b32 s10, v254, 52
	s_cselect_b64 s[8:9], -1, 0
	v_lshl_or_b32 v186, s54, 6, v19
	s_mov_b32 s58, 0
	v_cmp_eq_u32_e64 s[36:37], 0, v18
	v_mov_b32_e32 v161, v1
	v_lshl_add_u32 v162, v4, 1, v2
	v_mov_b32_e32 v163, v1
	v_add_u32_e32 v187, 0, v20
	v_readlane_b32 s6, v254, 26
	s_mov_b32 s27, s10
	s_barrier
	v_readlane_b32 s11, v254, 53
	s_branch .LBB0_669

; #define PG8_STAGE(bufoff, gbase, voff) do { _Pragma("unroll") for (int _i = 0; _i < 2; ++_i) \
;         __builtin_amdgcn_global_load_lds((const unsigned*)((const char*)(gbase) + (voff)[_i]), (PG8_LAS unsigned*)(lds + (bufoff) + ldsw + _i * 8192), 16, 0, 0); } while (0)
; #define PG8_LDA(dst, b, h) do { _Pragma("unroll") for (int m = 0; m < 4; ++m) _Pragma("unroll") for (int k = 0; k < 2; ++k) dst[m][k] = *(const PG8_LAS bf16x8*)(lds + PG8_SA(b, h) + aoff + m * 2048 + k * 1024); } while (0)
; #define PG8_LDB(dst, b, h) do { _Pragma("unroll") for (int n = 0; n < 2; ++n) _Pragma("unroll") for (int k = 0; k < 2; ++k) dst[n][k] = *(const PG8_LAS bf16x8*)(lds + PG8_SB(b, h) + boff + n * 2048 + k * 1024); } while (0)
; #define PG8_MMA(ai, bj, At, Bt) do { __builtin_amdgcn_s_setprio(1); _Pragma("unroll") for (int m = 0; m < 4; ++m) _Pragma("unroll") for (int n = 0; n < 2; ++n) _Pragma("unroll") for (int k = 0; k < 2; ++k) \
;         acc[ai][bj][m][n] = __builtin_amdgcn_mfma_f32_16x16x32_bf16(Bt[n][k], At[m][k], acc[ai][bj][m][n], 0, 0, 0); __builtin_amdgcn_s_setprio(0); } while (0)
; #define PG8_WAIT_V(n) asm volatile("s_waitcnt vmcnt(" #n ")" ::: "memory")
; #define PG8_WAIT_L(n) asm volatile("s_waitcnt lgkmcnt(" #n ")" ::: "memory")
; template <class Epi, class Sched, bool ALIGN_EPI = false, bool SP2 = false>
; __device__ __forceinline__ void gemm_phase(PG8_LAS unsigned char* lds, const Gemm g, const Sched& S, const Epi& E) {
;     ...
;             const bool last = (t == nt - 2);
;             const char* a1 = cA + (size_t)(t + 1) * kstep;
;             const char* a2 = last ? nA : cA + (size_t)(t + 2) * kstep; const char* b2 = last ? nB : cB + (size_t)(t + 2) * kstep;
;             const char* a3 = a2 + kstep; const char* b3 = b2 + kstep;
;             if (last && has_next) S.a_ready(nxt);
;             if constexpr (SP2) {
;             PG8_LDB(B0, 0, 0); PG8_LDB(B1, 0, 1); PG8_SCHED; PG8_LDA(At, 0, 0); PG8_STAGE(PG8_SA(1, 1), a1 + hstep, voffA);
;             PG8_WAIT_V(8); PG8_WAIT_L(0); PG8_BAR; PG8_MMA(0, 0, At, B0); PG8_MMA(0, 1, At, B1); PG8_BAR; PG8_SCHED;
;             PG8_LDA(At, 0, 1); PG8_STAGE(PG8_SB(0, 0), b2, voffB); PG8_STAGE(PG8_SB(0, 1), b2 + hstep, voffB); PG8_STAGE(PG8_SA(0, 0), a2, voffA);
;             PG8_WAIT_V(8); PG8_WAIT_L(0); PG8_BAR; PG8_MMA(1, 0, At, B0); PG8_MMA(1, 1, At, B1); PG8_BAR; PG8_SCHED;
.Lpeel_p3:
	s_add_u32 s30, s44, 0xfffc0080
	s_addc_u32 s31, s45, -1
	s_add_i32 s62, 0, 0x10000
	s_cmp_eq_u32 s61, 12
	s_cselect_b32 s49, s15, s31
	s_cselect_b32 s48, s34, s30
	s_cselect_b32 s47, s11, s60
	s_cselect_b32 s46, s35, s59
	s_add_i32 s63, 0, 0x14000
	v_add_u32_e32 v134, s62, v185
	v_add_u32_e32 v168, s63, v185
	ds_read_b128 v[114:117], v134
	ds_read_b128 v[118:121], v134 offset:1024
	ds_read_b128 v[126:129], v134 offset:2048
	ds_read_b128 v[134:137], v134 offset:3072
	ds_read_b128 v[146:149], v168
	ds_read_b128 v[150:153], v168 offset:1024
	ds_read_b128 v[164:167], v168 offset:2048
	ds_read_b128 v[168:171], v168 offset:3072
	v_lshl_add_u64 v[210:211], s[44:45], 0, v[160:161]
	s_add_i32 m0, s50, 0xc000
	ds_read_b128 v[172:175], v187
	ds_read_b128 v[176:179], v187 offset:1024
	ds_read_b128 v[180:183], v187 offset:2048
	ds_read_b128 v[188:191], v187 offset:3072
	ds_read_b128 v[198:201], v187 offset:4096
	ds_read_b128 v[202:205], v187 offset:5120
	ds_read_b128 v[206:209], v187 offset:6144
	ds_read_b128 v[222:225], v187 offset:7168
	global_load_lds_dwordx4 v[210:211], off
	v_lshl_add_u64 v[210:211], s[44:45], 0, v[162:163]
	s_add_i32 m0, s50, 0xe000
	s_nop 0
	global_load_lds_dwordx4 v[210:211], off
	s_waitcnt vmcnt(63)
	s_waitcnt lgkmcnt(0)
	s_barrier
	s_setprio 1
	s_waitcnt lgkmcnt(0)
	v_mfma_f32_16x16x32_bf16 v[142:145], v[114:117], v[172:175], 0
	v_mfma_f32_16x16x32_bf16 v[138:141], v[126:129], v[172:175], 0
	v_mfma_f32_16x16x32_bf16 v[110:113], v[114:117], v[180:183], 0
	v_mfma_f32_16x16x32_bf16 v[106:109], v[126:129], v[180:183], 0
	v_mfma_f32_16x16x32_bf16 v[94:97], v[114:117], v[198:201], 0
	v_mfma_f32_16x16x32_bf16 v[90:93], v[126:129], v[198:201], 0
	v_mfma_f32_16x16x32_bf16 v[78:81], v[114:117], v[206:209], 0
	v_mfma_f32_16x16x32_bf16 v[74:77], v[126:129], v[206:209], 0
	v_mfma_f32_16x16x32_bf16 v[142:145], v[118:121], v[176:179], v[142:145]
	v_mfma_f32_16x16x32_bf16 v[138:141], v[134:137], v[176:179], v[138:141]
	v_mfma_f32_16x16x32_bf16 v[110:113], v[118:121], v[188:191], v[110:113]
	v_mfma_f32_16x16x32_bf16 v[106:109], v[134:137], v[188:191], v[106:109]
	v_mfma_f32_16x16x32_bf16 v[94:97], v[118:121], v[202:205], v[94:97]
	v_mfma_f32_16x16x32_bf16 v[90:93], v[134:137], v[202:205], v[90:93]
	v_mfma_f32_16x16x32_bf16 v[78:81], v[118:121], v[222:225], v[78:81]
	v_mfma_f32_16x16x32_bf16 v[74:77], v[134:137], v[222:225], v[74:77]
	s_setprio 0
	s_setprio 1
	v_mfma_f32_16x16x32_bf16 v[130:133], v[146:149], v[172:175], 0
	v_mfma_f32_16x16x32_bf16 v[122:125], v[164:167], v[172:175], 0
	v_mfma_f32_16x16x32_bf16 v[102:105], v[146:149], v[180:183], 0
	v_mfma_f32_16x16x32_bf16 v[98:101], v[164:167], v[180:183], 0
	v_mfma_f32_16x16x32_bf16 v[86:89], v[146:149], v[198:201], 0
	v_mfma_f32_16x16x32_bf16 v[82:85], v[164:167], v[198:201], 0
	v_mfma_f32_16x16x32_bf16 v[70:73], v[146:149], v[206:209], 0
	v_mfma_f32_16x16x32_bf16 v[66:69], v[164:167], v[206:209], 0
	v_mfma_f32_16x16x32_bf16 v[130:133], v[150:153], v[176:179], v[130:133]
	v_mfma_f32_16x16x32_bf16 v[122:125], v[168:171], v[176:179], v[122:125]
	v_mfma_f32_16x16x32_bf16 v[102:105], v[150:153], v[188:191], v[102:105]
	v_mfma_f32_16x16x32_bf16 v[98:101], v[168:171], v[188:191], v[98:101]
	v_mfma_f32_16x16x32_bf16 v[86:89], v[150:153], v[202:205], v[86:89]
	v_mfma_f32_16x16x32_bf16 v[82:85], v[168:171], v[202:205], v[82:85]
	v_mfma_f32_16x16x32_bf16 v[70:73], v[150:153], v[222:225], v[70:73]
	v_mfma_f32_16x16x32_bf16 v[66:69], v[168:171], v[222:225], v[66:69]
	s_setprio 0
	s_barrier
	s_add_i32 s30, s62, s33
	v_lshl_add_u64 v[210:211], s[46:47], 0, v[0:1]
	s_mov_b32 m0, s30
	ds_read_b128 v[172:175], v187 offset:16384
	ds_read_b128 v[176:179], v187 offset:17408
	ds_read_b128 v[180:183], v187 offset:18432
	ds_read_b128 v[188:191], v187 offset:19456
	ds_read_b128 v[198:201], v187 offset:20480
	ds_read_b128 v[202:205], v187 offset:21504
	ds_read_b128 v[206:209], v187 offset:22528
	ds_read_b128 v[222:225], v187 offset:23552
	global_load_lds_dwordx4 v[210:211], off
	s_add_i32 m0, s30, 0x2000
	s_add_u32 s30, s46, 0x40000
	v_lshl_add_u64 v[226:227], s[46:47], 0, v[154:155]
	s_addc_u32 s31, s47, 0
	s_add_i32 s62, s63, s33
	global_load_lds_dwordx4 v[226:227], off
	v_lshl_add_u64 v[228:229], s[30:31], 0, v[0:1]
	s_mov_b32 m0, s62
	v_lshl_add_u64 v[230:231], s[48:49], 0, v[156:157]
	global_load_lds_dwordx4 v[228:229], off
	v_lshl_add_u64 v[228:229], s[30:31], 0, v[154:155]
	s_add_i32 m0, s62, 0x2000
	s_nop 0
	global_load_lds_dwordx4 v[228:229], off
	v_lshl_add_u64 v[228:229], s[48:49], 0, v[158:159]
	s_mov_b32 m0, s50
	s_nop 0
	global_load_lds_dwordx4 v[228:229], off
	s_mov_b32 m0, s51
	s_nop 0
	global_load_lds_dwordx4 v[230:231], off
	s_waitcnt vmcnt(63)
	s_waitcnt lgkmcnt(0)
	s_barrier
; #define PG8_STAGE(bufoff, gbase, voff) do { _Pragma("unroll") for (int _i = 0; _i < 2; ++_i) \
;         __builtin_amdgcn_global_load_lds((const unsigned*)((const char*)(gbase) + (voff)[_i]), (PG8_LAS unsigned*)(lds + (bufoff) + ldsw + _i * 8192), 16, 0, 0); } while (0)
; #define PG8_LDA(dst, b, h) do { _Pragma("unroll") for (int m = 0; m < 4; ++m) _Pragma("unroll") for (int k = 0; k < 2; ++k) dst[m][k] = *(const PG8_LAS bf16x8*)(lds + PG8_SA(b, h) + aoff + m * 2048 + k * 1024); } while (0)
; #define PG8_LDB(dst, b, h) do { _Pragma("unroll") for (int n = 0; n < 2; ++n) _Pragma("unroll") for (int k = 0; k < 2; ++k) dst[n][k] = *(const PG8_LAS bf16x8*)(lds + PG8_SB(b, h) + boff + n * 2048 + k * 1024); } while (0)
; #define PG8_MMA(ai, bj, At, Bt) do { __builtin_amdgcn_s_setprio(1); _Pragma("unroll") for (int m = 0; m < 4; ++m) _Pragma("unroll") for (int n = 0; n < 2; ++n) _Pragma("unroll") for (int k = 0; k < 2; ++k) \
;         acc[ai][bj][m][n] = __builtin_amdgcn_mfma_f32_16x16x32_bf16(Bt[n][k], At[m][k], acc[ai][bj][m][n], 0, 0, 0); __builtin_amdgcn_s_setprio(0); } while (0)
; #define PG8_WAIT_V(n) asm volatile("s_waitcnt vmcnt(" #n ")" ::: "memory")
; #define PG8_WAIT_L(n) asm volatile("s_waitcnt lgkmcnt(" #n ")" ::: "memory")
; #define PG8_BAR __builtin_amdgcn_s_barrier()
; #define PG8_SCHED __builtin_amdgcn_sched_barrier(0)
; template <class Epi, class Sched, bool ALIGN_EPI = false, bool SP2 = false>
; __device__ __forceinline__ void gemm_phase(PG8_LAS unsigned char* lds, const Gemm g, const Sched& S, const Epi& E) {
;     ...
;             PG8_WAIT_V(8); PG8_WAIT_L(0); PG8_BAR; PG8_MMA(1, 0, At, B0); PG8_MMA(1, 1, At, B1); PG8_BAR; PG8_SCHED;
;             PG8_LDB(B0, 1, 0); PG8_LDB(B1, 1, 1); PG8_SCHED; PG8_LDA(At, 1, 0); PG8_STAGE(PG8_SA(0, 1), a2 + hstep, voffA);
;             PG8_WAIT_V(8); PG8_WAIT_L(0); PG8_BAR; PG8_MMA(0, 0, At, B0); PG8_MMA(0, 1, At, B1); PG8_BAR; PG8_SCHED;
	s_setprio 1
	s_waitcnt lgkmcnt(0)
	v_mfma_f32_16x16x32_bf16 v[62:65], v[114:117], v[172:175], 0
	v_mfma_f32_16x16x32_bf16 v[58:61], v[126:129], v[172:175], 0
	v_mfma_f32_16x16x32_bf16 v[46:49], v[114:117], v[180:183], 0
	v_mfma_f32_16x16x32_bf16 v[42:45], v[126:129], v[180:183], 0
	v_mfma_f32_16x16x32_bf16 v[30:33], v[114:117], v[198:201], 0
	v_mfma_f32_16x16x32_bf16 v[26:29], v[126:129], v[198:201], 0
	v_mfma_f32_16x16x32_bf16 v[14:17], v[114:117], v[206:209], 0
	v_mfma_f32_16x16x32_bf16 v[10:13], v[126:129], v[206:209], 0
	v_mfma_f32_16x16x32_bf16 v[62:65], v[118:121], v[176:179], v[62:65]
	v_mfma_f32_16x16x32_bf16 v[58:61], v[134:137], v[176:179], v[58:61]
	v_mfma_f32_16x16x32_bf16 v[46:49], v[118:121], v[188:191], v[46:49]
	v_mfma_f32_16x16x32_bf16 v[42:45], v[134:137], v[188:191], v[42:45]
	v_mfma_f32_16x16x32_bf16 v[30:33], v[118:121], v[202:205], v[30:33]
	v_mfma_f32_16x16x32_bf16 v[26:29], v[134:137], v[202:205], v[26:29]
	v_mfma_f32_16x16x32_bf16 v[14:17], v[118:121], v[222:225], v[14:17]
	v_mfma_f32_16x16x32_bf16 v[10:13], v[134:137], v[222:225], v[10:13]
	s_setprio 0
	s_setprio 1
	v_mfma_f32_16x16x32_bf16 v[54:57], v[146:149], v[172:175], 0
	v_mfma_f32_16x16x32_bf16 v[50:53], v[164:167], v[172:175], 0
	v_mfma_f32_16x16x32_bf16 v[38:41], v[146:149], v[180:183], 0
	v_mfma_f32_16x16x32_bf16 v[34:37], v[164:167], v[180:183], 0
	v_mfma_f32_16x16x32_bf16 v[22:25], v[146:149], v[198:201], 0
	v_mfma_f32_16x16x32_bf16 v[18:21], v[164:167], v[198:201], 0
	v_mfma_f32_16x16x32_bf16 v[6:9], v[146:149], v[206:209], 0
	v_mfma_f32_16x16x32_bf16 v[2:5], v[164:167], v[206:209], 0
	v_mfma_f32_16x16x32_bf16 v[54:57], v[150:153], v[176:179], v[54:57]
	v_mfma_f32_16x16x32_bf16 v[50:53], v[168:171], v[176:179], v[50:53]
	v_mfma_f32_16x16x32_bf16 v[38:41], v[150:153], v[188:191], v[38:41]
	v_mfma_f32_16x16x32_bf16 v[34:37], v[168:171], v[188:191], v[34:37]
	v_mfma_f32_16x16x32_bf16 v[22:25], v[150:153], v[202:205], v[22:25]
	v_mfma_f32_16x16x32_bf16 v[18:21], v[168:171], v[202:205], v[18:21]
	v_mfma_f32_16x16x32_bf16 v[6:9], v[150:153], v[222:225], v[6:9]
	v_mfma_f32_16x16x32_bf16 v[2:5], v[168:171], v[222:225], v[2:5]
	s_setprio 0
	s_barrier
	s_add_i32 s62, 0, 0x18000
	s_add_i32 s63, 0, 0x1c000
	v_add_u32_e32 v134, s62, v185
	v_add_u32_e32 v168, s63, v185
	ds_read_b128 v[114:117], v134
	ds_read_b128 v[118:121], v134 offset:1024
	ds_read_b128 v[126:129], v134 offset:2048
	ds_read_b128 v[134:137], v134 offset:3072
	ds_read_b128 v[146:149], v168
	ds_read_b128 v[150:153], v168 offset:1024
	ds_read_b128 v[164:167], v168 offset:2048
	ds_read_b128 v[168:171], v168 offset:3072
	s_add_u32 s30, s48, 0x40000
	s_addc_u32 s31, s49, 0
	s_mov_b32 m0, s52
	v_lshl_add_u64 v[232:233], s[30:31], 0, v[158:159]
	ds_read_b128 v[172:175], v187 offset:32768
	ds_read_b128 v[176:179], v187 offset:33792
	ds_read_b128 v[180:183], v187 offset:34816
	ds_read_b128 v[188:191], v187 offset:35840
	ds_read_b128 v[198:201], v187 offset:36864
	ds_read_b128 v[202:205], v187 offset:37888
	ds_read_b128 v[206:209], v187 offset:38912
	ds_read_b128 v[222:225], v187 offset:39936
	global_load_lds_dwordx4 v[232:233], off
	v_lshl_add_u64 v[232:233], s[30:31], 0, v[156:157]
	s_mov_b32 m0, s53
	s_nop 0
	global_load_lds_dwordx4 v[232:233], off
	s_waitcnt vmcnt(8)
	s_waitcnt lgkmcnt(0)
	s_barrier
	s_setprio 1
	s_waitcnt lgkmcnt(0)
	v_mfma_f32_16x16x32_bf16 v[142:145], v[114:117], v[172:175], v[142:145]
	v_mfma_f32_16x16x32_bf16 v[138:141], v[126:129], v[172:175], v[138:141]
	v_mfma_f32_16x16x32_bf16 v[110:113], v[114:117], v[180:183], v[110:113]
	v_mfma_f32_16x16x32_bf16 v[106:109], v[126:129], v[180:183], v[106:109]
	v_mfma_f32_16x16x32_bf16 v[94:97], v[114:117], v[198:201], v[94:97]
	v_mfma_f32_16x16x32_bf16 v[90:93], v[126:129], v[198:201], v[90:93]
	v_mfma_f32_16x16x32_bf16 v[78:81], v[114:117], v[206:209], v[78:81]
	v_mfma_f32_16x16x32_bf16 v[74:77], v[126:129], v[206:209], v[74:77]
	v_mfma_f32_16x16x32_bf16 v[142:145], v[118:121], v[176:179], v[142:145]
	v_mfma_f32_16x16x32_bf16 v[138:141], v[134:137], v[176:179], v[138:141]
	v_mfma_f32_16x16x32_bf16 v[110:113], v[118:121], v[188:191], v[110:113]
	v_mfma_f32_16x16x32_bf16 v[106:109], v[134:137], v[188:191], v[106:109]
	v_mfma_f32_16x16x32_bf16 v[94:97], v[118:121], v[202:205], v[94:97]
	v_mfma_f32_16x16x32_bf16 v[90:93], v[134:137], v[202:205], v[90:93]
	v_mfma_f32_16x16x32_bf16 v[78:81], v[118:121], v[222:225], v[78:81]
	v_mfma_f32_16x16x32_bf16 v[74:77], v[134:137], v[222:225], v[74:77]
	s_setprio 0
	s_setprio 1
	v_mfma_f32_16x16x32_bf16 v[130:133], v[146:149], v[172:175], v[130:133]
	v_mfma_f32_16x16x32_bf16 v[122:125], v[164:167], v[172:175], v[122:125]
	v_mfma_f32_16x16x32_bf16 v[102:105], v[146:149], v[180:183], v[102:105]
	v_mfma_f32_16x16x32_bf16 v[98:101], v[164:167], v[180:183], v[98:101]
	v_mfma_f32_16x16x32_bf16 v[86:89], v[146:149], v[198:201], v[86:89]
	v_mfma_f32_16x16x32_bf16 v[82:85], v[164:167], v[198:201], v[82:85]
	v_mfma_f32_16x16x32_bf16 v[70:73], v[146:149], v[206:209], v[70:73]
	v_mfma_f32_16x16x32_bf16 v[66:69], v[164:167], v[206:209], v[66:69]
	v_mfma_f32_16x16x32_bf16 v[130:133], v[150:153], v[176:179], v[130:133]
	v_mfma_f32_16x16x32_bf16 v[122:125], v[168:171], v[176:179], v[122:125]
	v_mfma_f32_16x16x32_bf16 v[102:105], v[150:153], v[188:191], v[102:105]
	v_mfma_f32_16x16x32_bf16 v[98:101], v[168:171], v[188:191], v[98:101]
	v_mfma_f32_16x16x32_bf16 v[86:89], v[150:153], v[202:205], v[86:89]
	v_mfma_f32_16x16x32_bf16 v[82:85], v[168:171], v[202:205], v[82:85]
	v_mfma_f32_16x16x32_bf16 v[70:73], v[150:153], v[222:225], v[70:73]
	v_mfma_f32_16x16x32_bf16 v[66:69], v[168:171], v[222:225], v[66:69]
	s_setprio 0
	s_barrier
; #define PG8_STAGE(bufoff, gbase, voff) do { _Pragma("unroll") for (int _i = 0; _i < 2; ++_i) \
;         __builtin_amdgcn_global_load_lds((const unsigned*)((const char*)(gbase) + (voff)[_i]), (PG8_LAS unsigned*)(lds + (bufoff) + ldsw + _i * 8192), 16, 0, 0); } while (0)
; #define PG8_LDA(dst, b, h) do { _Pragma("unroll") for (int m = 0; m < 4; ++m) _Pragma("unroll") for (int k = 0; k < 2; ++k) dst[m][k] = *(const PG8_LAS bf16x8*)(lds + PG8_SA(b, h) + aoff + m * 2048 + k * 1024); } while (0)
; #define PG8_MMA(ai, bj, At, Bt) do { __builtin_amdgcn_s_setprio(1); _Pragma("unroll") for (int m = 0; m < 4; ++m) _Pragma("unroll") for (int n = 0; n < 2; ++n) _Pragma("unroll") for (int k = 0; k < 2; ++k) \
;         acc[ai][bj][m][n] = __builtin_amdgcn_mfma_f32_16x16x32_bf16(Bt[n][k], At[m][k], acc[ai][bj][m][n], 0, 0, 0); __builtin_amdgcn_s_setprio(0); } while (0)
; #define PG8_WAIT_V(n) asm volatile("s_waitcnt vmcnt(" #n ")" ::: "memory")
; #define PG8_WAIT_L(n) asm volatile("s_waitcnt lgkmcnt(" #n ")" ::: "memory")
; #define PG8_BAR __builtin_amdgcn_s_barrier()
; #define PG8_SCHED __builtin_amdgcn_sched_barrier(0)
; template <class Epi, class Sched, bool ALIGN_EPI = false, bool SP2 = false>
; __device__ __forceinline__ void gemm_phase(PG8_LAS unsigned char* lds, const Gemm g, const Sched& S, const Epi& E) {
;     ...
;         for (int t = 0; t < nt; t += 2) {
;             const bool last = (t == nt - 2);
;             const char* a1 = cA + (size_t)(t + 1) * kstep;
;             const char* a2 = last ? nA : cA + (size_t)(t + 2) * kstep; const char* b2 = last ? nB : cB + (size_t)(t + 2) * kstep;
;     ...
;             PG8_LDA(At, 1, 1); PG8_STAGE(PG8_SB(1, 0), b3, voffB); PG8_STAGE(PG8_SB(1, 1), b3 + hstep, voffB); PG8_STAGE(PG8_SA(1, 0), a3, voffA);
;             PG8_WAIT_V(8); PG8_WAIT_L(0); PG8_BAR; PG8_MMA(1, 0, At, B0); PG8_MMA(1, 1, At, B1); PG8_BAR; PG8_SCHED;
	s_add_i32 s30, s62, s33
	v_lshl_add_u64 v[210:211], v[210:211], 0, s[0:1]
	s_mov_b32 m0, s30
	ds_read_b128 v[172:175], v187 offset:49152
	ds_read_b128 v[176:179], v187 offset:50176
	ds_read_b128 v[180:183], v187 offset:51200
	ds_read_b128 v[188:191], v187 offset:52224
	ds_read_b128 v[198:201], v187 offset:53248
	ds_read_b128 v[202:205], v187 offset:54272
	ds_read_b128 v[206:209], v187 offset:55296
	ds_read_b128 v[222:225], v187 offset:56320
	global_load_lds_dwordx4 v[210:211], off
	s_add_i32 m0, s30, 0x2000
	s_add_u32 s30, s46, 0x40080
	v_lshl_add_u64 v[210:211], v[226:227], 0, s[0:1]
	s_addc_u32 s31, s47, 0
	s_add_i32 s46, s63, s33
	global_load_lds_dwordx4 v[210:211], off
	v_lshl_add_u64 v[210:211], s[30:31], 0, v[0:1]
	s_mov_b32 m0, s46
	s_nop 0
	global_load_lds_dwordx4 v[210:211], off
	v_lshl_add_u64 v[210:211], s[30:31], 0, v[154:155]
	s_add_i32 m0, s46, 0x2000
	s_nop 0
	global_load_lds_dwordx4 v[210:211], off
	v_lshl_add_u64 v[210:211], v[228:229], 0, s[0:1]
	s_mov_b32 m0, s56
	s_nop 0
	global_load_lds_dwordx4 v[210:211], off
	v_lshl_add_u64 v[210:211], v[230:231], 0, s[0:1]
	s_mov_b32 m0, s57
	s_nop 0
	global_load_lds_dwordx4 v[210:211], off
	s_waitcnt vmcnt(8)
	s_waitcnt lgkmcnt(0)
	s_barrier
	s_setprio 1
	s_waitcnt lgkmcnt(0)
	v_mfma_f32_16x16x32_bf16 v[62:65], v[114:117], v[172:175], v[62:65]
	v_mfma_f32_16x16x32_bf16 v[58:61], v[126:129], v[172:175], v[58:61]
	v_mfma_f32_16x16x32_bf16 v[46:49], v[114:117], v[180:183], v[46:49]
	v_mfma_f32_16x16x32_bf16 v[42:45], v[126:129], v[180:183], v[42:45]
	v_mfma_f32_16x16x32_bf16 v[30:33], v[114:117], v[198:201], v[30:33]
	v_mfma_f32_16x16x32_bf16 v[26:29], v[126:129], v[198:201], v[26:29]
	v_mfma_f32_16x16x32_bf16 v[14:17], v[114:117], v[206:209], v[14:17]
	v_mfma_f32_16x16x32_bf16 v[10:13], v[126:129], v[206:209], v[10:13]
	v_mfma_f32_16x16x32_bf16 v[62:65], v[118:121], v[176:179], v[62:65]
	v_mfma_f32_16x16x32_bf16 v[58:61], v[134:137], v[176:179], v[58:61]
	v_mfma_f32_16x16x32_bf16 v[46:49], v[118:121], v[188:191], v[46:49]
	v_mfma_f32_16x16x32_bf16 v[42:45], v[134:137], v[188:191], v[42:45]
	v_mfma_f32_16x16x32_bf16 v[30:33], v[118:121], v[202:205], v[30:33]
	v_mfma_f32_16x16x32_bf16 v[26:29], v[134:137], v[202:205], v[26:29]
	v_mfma_f32_16x16x32_bf16 v[14:17], v[118:121], v[222:225], v[14:17]
	v_mfma_f32_16x16x32_bf16 v[10:13], v[134:137], v[222:225], v[10:13]
	s_setprio 0
	s_setprio 1
	v_mfma_f32_16x16x32_bf16 v[54:57], v[146:149], v[172:175], v[54:57]
	v_mfma_f32_16x16x32_bf16 v[50:53], v[164:167], v[172:175], v[50:53]
	v_mfma_f32_16x16x32_bf16 v[38:41], v[146:149], v[180:183], v[38:41]
	v_mfma_f32_16x16x32_bf16 v[34:37], v[164:167], v[180:183], v[34:37]
	v_mfma_f32_16x16x32_bf16 v[22:25], v[146:149], v[198:201], v[22:25]
	v_mfma_f32_16x16x32_bf16 v[18:21], v[164:167], v[198:201], v[18:21]
	v_mfma_f32_16x16x32_bf16 v[6:9], v[146:149], v[206:209], v[6:9]
	v_mfma_f32_16x16x32_bf16 v[2:5], v[164:167], v[206:209], v[2:5]
	v_mfma_f32_16x16x32_bf16 v[54:57], v[150:153], v[176:179], v[54:57]
	v_mfma_f32_16x16x32_bf16 v[50:53], v[168:171], v[176:179], v[50:53]
	v_mfma_f32_16x16x32_bf16 v[38:41], v[150:153], v[188:191], v[38:41]
	v_mfma_f32_16x16x32_bf16 v[34:37], v[168:171], v[188:191], v[34:37]
	v_mfma_f32_16x16x32_bf16 v[22:25], v[150:153], v[202:205], v[22:25]
	v_mfma_f32_16x16x32_bf16 v[18:21], v[168:171], v[202:205], v[18:21]
	v_mfma_f32_16x16x32_bf16 v[6:9], v[150:153], v[222:225], v[6:9]
	v_mfma_f32_16x16x32_bf16 v[2:5], v[168:171], v[222:225], v[2:5]
	s_setprio 0
	s_barrier
	s_add_i32 s61, s61, 2
	s_add_u32 s44, s44, 0x100
	s_addc_u32 s45, s45, 0
	s_add_u32 s59, s59, 0x100
	s_addc_u32 s60, s60, 0
	s_cmp_gt_u32 s61, 13
	s_cbranch_scc0 .LBB0_676
	s_branch .Lpeel_exit_p3

; #define PG8_STAGE(bufoff, gbase, voff) do { _Pragma("unroll") for (int _i = 0; _i < 2; ++_i) \
;         __builtin_amdgcn_global_load_lds((const unsigned*)((const char*)(gbase) + (voff)[_i]), (PG8_LAS unsigned*)(lds + (bufoff) + ldsw + _i * 8192), 16, 0, 0); } while (0)
; #define PG8_WAIT_V(n) asm volatile("s_waitcnt vmcnt(" #n ")" ::: "memory")
; #define PG8_BAR __builtin_amdgcn_s_barrier()
; template <class Epi, class Sched, bool ALIGN_EPI = false, bool SP2 = false>
; __device__ __forceinline__ void gemm_phase(PG8_LAS unsigned char* lds, const Gemm g, const Sched& S, const Epi& E) {
;     ...
;     for (int i = 0; i < 2; ++i) { int R, C; stage_rc(tid * 16 + i * 8192, R, C); const int Rb = Epi::PERM ? ((R & ~31) + perm32(R & 31)) : R;
;         voffA[i] = (unsigned)(R * K + C) * 2u; voffB[i] = (unsigned)(Rb * K + C) * 2u; }
;     const size_t kstep = (size_t)(BK * 2);
;     const size_t hstep = (size_t)HALF * K * 2;
;     const size_t tstep = 2 * hstep;
;     const unsigned ldsw = (unsigned)wid * 1024u;
;     const int aoff = lds_byte(wr * 64 + fr, fq * 8), boff = lds_byte(wc * 32 + fr, fq * 8);
;     ...
;         PG8_STAGE(PG8_SB(0, 0), cB, voffB); PG8_STAGE(PG8_SB(0, 1), cB + hstep, voffB); PG8_STAGE(PG8_SA(0, 0), cA, voffA); PG8_STAGE(PG8_SA(0, 1), cA + hstep, voffA);
;         if (wr == 1) PG8_BAR;
;         PG8_WAIT_V(2); PG8_BAR;
;         PG8_STAGE(PG8_SB(1, 0), cB + kstep, voffB); PG8_STAGE(PG8_SA(1, 0), cA + kstep, voffA); PG8_STAGE(PG8_SB(1, 1), cB + hstep + kstep, voffB);
;         PG8_WAIT_V(6); PG8_BAR;
.LBB0_775:
	v_readlane_b32 s46, v254, 33
	s_lshl_b32 s9, s9, 5
	v_mov_b32_e32 v139, v1
	v_readlane_b32 s47, v254, 34
	s_and_b32 s15, s9, 0x60
	s_add_i32 m0, s52, 0x18000
	v_lshl_add_u64 v[2:3], v[2:3], 0, s[0:1]
	v_lshl_add_u64 v[14:15], s[46:47], 0, v[138:139]
	v_mov_b32_e32 v143, v1
	s_lshl_b32 s14, s8, 13
	s_lshl_b32 s9, s15, 7
	s_waitcnt vmcnt(2)
	s_barrier
	global_load_lds_dwordx4 v[2:3], off
	v_lshl_add_u64 v[2:3], v[4:5], 0, s[0:1]
	s_add_i32 m0, s52, 0x1a000
	s_add_i32 s56, s52, 0x8000
	s_add_i32 s57, s52, 0xa000
	v_lshl_add_u64 v[16:17], s[46:47], 0, v[142:143]
	global_load_lds_dwordx4 v[2:3], off
	v_lshl_add_u64 v[2:3], v[14:15], 0, s[0:1]
	s_mov_b32 m0, s56
	s_add_u32 s10, s48, 0x40080
	global_load_lds_dwordx4 v[2:3], off
	v_lshl_add_u64 v[2:3], v[16:17], 0, s[0:1]
	s_mov_b32 m0, s57
	s_addc_u32 s11, s49, 0
	global_load_lds_dwordx4 v[2:3], off
	s_add_i32 m0, s52, 0x1c000
	v_lshl_add_u64 v[2:3], s[10:11], 0, v[140:141]
	global_load_lds_dwordx4 v[2:3], off
	v_lshl_add_u64 v[2:3], s[10:11], 0, v[144:145]
	s_add_i32 m0, s52, 0x1e000
	v_readlane_b32 s10, v252, 53
	global_load_lds_dwordx4 v[2:3], off
	v_lshrrev_b32_e32 v2, 1, v6
	v_and_b32_e32 v2, 24, v2
	v_and_b32_e32 v3, 15, v6
	v_lshlrev_b32_e32 v4, 1, v2
	v_lshl_or_b32 v156, s8, 6, v3
	v_lshl_or_b32 v4, v3, 6, v4
	v_lshlrev_b32_e32 v3, 2, v3
	v_and_b32_e32 v5, 32, v3
	v_readlane_b32 s11, v252, 54
	v_bitop3_b32 v157, v4, s9, v5 bitop3:0xde
	s_lshl_b32 s8, s8, 8
	s_add_i32 s9, 0, 0x22800
	v_lshl_add_u64 v[146:147], s[10:11], 0, v[0:1]
	v_lshlrev_b32_e32 v0, 14, v7
	s_add_i32 s8, s9, s8
	v_and_b32_e32 v0, 0xffff8000, v0
	v_add_u32_e32 v158, s8, v3
	v_lshl_add_u32 v0, v8, 11, v0
	v_and_b32_e32 v3, 1, v7
	v_lshl_or_b32 v0, v3, 6, v0
	v_lshl_add_u32 v148, v9, 1, v0
	v_lshlrev_b32_e32 v0, 14, v10
	v_and_b32_e32 v0, 0xffff8000, v0
	s_waitcnt vmcnt(0)
	v_lshl_add_u32 v0, v11, 11, v0
	v_and_b32_e32 v3, 1, v10
	v_bitop3_b32 v6, v4, s14, v5 bitop3:0xde
	s_cmpk_lt_u32 s6, 0x100
	v_lshl_or_b32 v0, v3, 6, v0
	v_readlane_b32 s20, v254, 30
	v_lshl_add_u32 v159, v154, 2, s9
	s_cselect_b64 s[8:9], -1, 0
	v_mov_b32_e32 v149, v1
	v_lshl_add_u32 v150, v12, 1, v0
	v_mov_b32_e32 v151, v1
	s_mov_b32 s34, 0
	v_add_u32_e32 v160, 0, v6
	s_lshl_b32 s6, s15, 1
	v_lshlrev_b32_e32 v0, 1, v2
	s_mov_b32 s58, s20
	v_readlane_b32 s35, v254, 27
	s_barrier
	v_readlane_b32 s21, v254, 31
	s_branch .LBB0_778

; #define PG8_STAGE(bufoff, gbase, voff) do { _Pragma("unroll") for (int _i = 0; _i < 2; ++_i) \
;         __builtin_amdgcn_global_load_lds((const unsigned*)((const char*)(gbase) + (voff)[_i]), (PG8_LAS unsigned*)(lds + (bufoff) + ldsw + _i * 8192), 16, 0, 0); } while (0)
; #define PG8_LDA(dst, b, h) do { _Pragma("unroll") for (int m = 0; m < 4; ++m) _Pragma("unroll") for (int k = 0; k < 2; ++k) dst[m][k] = *(const PG8_LAS bf16x8*)(lds + PG8_SA(b, h) + aoff + m * 2048 + k * 1024); } while (0)
; #define PG8_LDB(dst, b, h) do { _Pragma("unroll") for (int n = 0; n < 2; ++n) _Pragma("unroll") for (int k = 0; k < 2; ++k) dst[n][k] = *(const PG8_LAS bf16x8*)(lds + PG8_SB(b, h) + boff + n * 2048 + k * 1024); } while (0)
; #define PG8_MMA(ai, bj, At, Bt) do { __builtin_amdgcn_s_setprio(1); _Pragma("unroll") for (int m = 0; m < 4; ++m) _Pragma("unroll") for (int n = 0; n < 2; ++n) _Pragma("unroll") for (int k = 0; k < 2; ++k) \
;         acc[ai][bj][m][n] = __builtin_amdgcn_mfma_f32_16x16x32_bf16(Bt[n][k], At[m][k], acc[ai][bj][m][n], 0, 0, 0); __builtin_amdgcn_s_setprio(0); } while (0)
; #define PG8_WAIT_V(n) asm volatile("s_waitcnt vmcnt(" #n ")" ::: "memory")
; #define PG8_WAIT_L(n) asm volatile("s_waitcnt lgkmcnt(" #n ")" ::: "memory")
; template <class Epi, class Sched, bool ALIGN_EPI = false, bool SP2 = false>
; __device__ __forceinline__ void gemm_phase(PG8_LAS unsigned char* lds, const Gemm g, const Sched& S, const Epi& E) {
;     ...
;             const bool last = (t == nt - 2);
;             const char* a1 = cA + (size_t)(t + 1) * kstep;
;             const char* a2 = last ? nA : cA + (size_t)(t + 2) * kstep; const char* b2 = last ? nB : cB + (size_t)(t + 2) * kstep;
;             const char* a3 = a2 + kstep; const char* b3 = b2 + kstep;
;             if (last && has_next) S.a_ready(nxt);
;             if constexpr (SP2) {
;             PG8_LDB(B0, 0, 0); PG8_LDB(B1, 0, 1); PG8_SCHED; PG8_LDA(At, 0, 0); PG8_STAGE(PG8_SA(1, 1), a1 + hstep, voffA);
;             PG8_WAIT_V(8); PG8_WAIT_L(0); PG8_BAR; PG8_MMA(0, 0, At, B0); PG8_MMA(0, 1, At, B1); PG8_BAR; PG8_SCHED;
;             PG8_LDA(At, 0, 1); PG8_STAGE(PG8_SB(0, 0), b2, voffB); PG8_STAGE(PG8_SB(0, 1), b2 + hstep, voffB); PG8_STAGE(PG8_SA(0, 0), a2, voffA);
;             PG8_WAIT_V(8); PG8_WAIT_L(0); PG8_BAR; PG8_MMA(1, 0, At, B0); PG8_MMA(1, 1, At, B1); PG8_BAR; PG8_SCHED;
.Lpeel_p4:
	s_add_u32 s30, s46, 0xfffc0080
	s_addc_u32 s31, s47, -1
	s_add_i32 s65, 0, 0x10000
	s_cmp_eq_u32 s64, 12
	s_cselect_b32 s51, s15, s31
	s_cselect_b32 s50, s60, s30
	v_add_u32_e32 v152, s65, v157
	s_cselect_b32 s49, s11, s63
	s_cselect_b32 s48, s61, s62
	s_add_i32 s66, 0, 0x14000
	ds_read_b128 v[50:53], v152
	ds_read_b128 v[54:57], v152 offset:1024
	ds_read_b128 v[162:165], v152 offset:2048
	ds_read_b128 v[166:169], v152 offset:3072
	v_add_u32_e32 v152, s66, v157
	ds_read_b128 v[170:173], v152
	ds_read_b128 v[174:177], v152 offset:1024
	ds_read_b128 v[178:181], v152 offset:2048
	ds_read_b128 v[182:185], v152 offset:3072
	v_lshl_add_u64 v[152:153], s[46:47], 0, v[148:149]
	s_add_i32 m0, s52, 0xc000
	ds_read_b128 v[186:189], v160
	ds_read_b128 v[198:201], v160 offset:1024
	ds_read_b128 v[202:205], v160 offset:2048
	ds_read_b128 v[206:209], v160 offset:3072
	ds_read_b128 v[222:225], v160 offset:4096
	ds_read_b128 v[226:229], v160 offset:5120
	ds_read_b128 v[230:233], v160 offset:6144
	ds_read_b128 v[234:237], v160 offset:7168
	global_load_lds_dwordx4 v[152:153], off
	v_lshl_add_u64 v[152:153], s[46:47], 0, v[150:151]
	s_add_i32 m0, s52, 0xe000
	s_nop 0
	global_load_lds_dwordx4 v[152:153], off
	s_waitcnt vmcnt(63)
	s_waitcnt lgkmcnt(0)
	s_barrier
	s_setprio 1
	s_waitcnt lgkmcnt(0)
	v_mfma_f32_16x16x32_bf16 v[134:137], v[50:53], v[186:189], 0
	v_mfma_f32_16x16x32_bf16 v[126:129], v[162:165], v[186:189], 0
	v_mfma_f32_16x16x32_bf16 v[118:121], v[50:53], v[202:205], 0
	v_mfma_f32_16x16x32_bf16 v[110:113], v[162:165], v[202:205], 0
	v_mfma_f32_16x16x32_bf16 v[102:105], v[50:53], v[222:225], 0
	v_mfma_f32_16x16x32_bf16 v[94:97], v[162:165], v[222:225], 0
	v_mfma_f32_16x16x32_bf16 v[86:89], v[50:53], v[230:233], 0
	v_mfma_f32_16x16x32_bf16 v[78:81], v[162:165], v[230:233], 0
	v_mfma_f32_16x16x32_bf16 v[134:137], v[54:57], v[198:201], v[134:137]
	v_mfma_f32_16x16x32_bf16 v[126:129], v[166:169], v[198:201], v[126:129]
	v_mfma_f32_16x16x32_bf16 v[118:121], v[54:57], v[206:209], v[118:121]
	v_mfma_f32_16x16x32_bf16 v[110:113], v[166:169], v[206:209], v[110:113]
	v_mfma_f32_16x16x32_bf16 v[102:105], v[54:57], v[226:229], v[102:105]
	v_mfma_f32_16x16x32_bf16 v[94:97], v[166:169], v[226:229], v[94:97]
	v_mfma_f32_16x16x32_bf16 v[86:89], v[54:57], v[234:237], v[86:89]
	v_mfma_f32_16x16x32_bf16 v[78:81], v[166:169], v[234:237], v[78:81]
	s_setprio 0
	s_setprio 1
	v_mfma_f32_16x16x32_bf16 v[130:133], v[170:173], v[186:189], 0
	v_mfma_f32_16x16x32_bf16 v[122:125], v[178:181], v[186:189], 0
	v_mfma_f32_16x16x32_bf16 v[114:117], v[170:173], v[202:205], 0
	v_mfma_f32_16x16x32_bf16 v[106:109], v[178:181], v[202:205], 0
	v_mfma_f32_16x16x32_bf16 v[98:101], v[170:173], v[222:225], 0
	v_mfma_f32_16x16x32_bf16 v[90:93], v[178:181], v[222:225], 0
	v_mfma_f32_16x16x32_bf16 v[82:85], v[170:173], v[230:233], 0
	v_mfma_f32_16x16x32_bf16 v[74:77], v[178:181], v[230:233], 0
	v_mfma_f32_16x16x32_bf16 v[130:133], v[174:177], v[198:201], v[130:133]
	v_mfma_f32_16x16x32_bf16 v[122:125], v[182:185], v[198:201], v[122:125]
	v_mfma_f32_16x16x32_bf16 v[114:117], v[174:177], v[206:209], v[114:117]
	v_mfma_f32_16x16x32_bf16 v[106:109], v[182:185], v[206:209], v[106:109]
	v_mfma_f32_16x16x32_bf16 v[98:101], v[174:177], v[226:229], v[98:101]
	v_mfma_f32_16x16x32_bf16 v[90:93], v[182:185], v[226:229], v[90:93]
	v_mfma_f32_16x16x32_bf16 v[82:85], v[174:177], v[234:237], v[82:85]
	v_mfma_f32_16x16x32_bf16 v[74:77], v[182:185], v[234:237], v[74:77]
	s_setprio 0
	s_barrier
	s_add_i32 s30, s65, s33
	v_lshl_add_u64 v[152:153], s[48:49], 0, v[140:141]
	s_mov_b32 m0, s30
	ds_read_b128 v[186:189], v160 offset:16384
	ds_read_b128 v[198:201], v160 offset:17408
	ds_read_b128 v[202:205], v160 offset:18432
	ds_read_b128 v[206:209], v160 offset:19456
	ds_read_b128 v[222:225], v160 offset:20480
	ds_read_b128 v[226:229], v160 offset:21504
	ds_read_b128 v[230:233], v160 offset:22528
	ds_read_b128 v[234:237], v160 offset:23552
	global_load_lds_dwordx4 v[152:153], off
	s_add_i32 m0, s30, 0x2000
	s_add_u32 s30, s48, 0x40000
	v_lshl_add_u64 v[190:191], s[48:49], 0, v[144:145]
	s_addc_u32 s31, s49, 0
	s_add_i32 s65, s66, s33
	global_load_lds_dwordx4 v[190:191], off
	v_lshl_add_u64 v[210:211], s[30:31], 0, v[140:141]
	s_mov_b32 m0, s65
	v_lshl_add_u64 v[238:239], s[50:51], 0, v[142:143]
	global_load_lds_dwordx4 v[210:211], off
	v_lshl_add_u64 v[210:211], s[30:31], 0, v[144:145]
	s_add_i32 m0, s65, 0x2000
	s_nop 0
	global_load_lds_dwordx4 v[210:211], off
	v_lshl_add_u64 v[210:211], s[50:51], 0, v[138:139]
	s_mov_b32 m0, s52
	s_nop 0
	global_load_lds_dwordx4 v[210:211], off
	s_mov_b32 m0, s53
	s_nop 0
	global_load_lds_dwordx4 v[238:239], off
	s_waitcnt vmcnt(63)
	s_waitcnt lgkmcnt(0)
	s_barrier
; #define PG8_STAGE(bufoff, gbase, voff) do { _Pragma("unroll") for (int _i = 0; _i < 2; ++_i) \
;         __builtin_amdgcn_global_load_lds((const unsigned*)((const char*)(gbase) + (voff)[_i]), (PG8_LAS unsigned*)(lds + (bufoff) + ldsw + _i * 8192), 16, 0, 0); } while (0)
; #define PG8_LDA(dst, b, h) do { _Pragma("unroll") for (int m = 0; m < 4; ++m) _Pragma("unroll") for (int k = 0; k < 2; ++k) dst[m][k] = *(const PG8_LAS bf16x8*)(lds + PG8_SA(b, h) + aoff + m * 2048 + k * 1024); } while (0)
; #define PG8_LDB(dst, b, h) do { _Pragma("unroll") for (int n = 0; n < 2; ++n) _Pragma("unroll") for (int k = 0; k < 2; ++k) dst[n][k] = *(const PG8_LAS bf16x8*)(lds + PG8_SB(b, h) + boff + n * 2048 + k * 1024); } while (0)
; #define PG8_MMA(ai, bj, At, Bt) do { __builtin_amdgcn_s_setprio(1); _Pragma("unroll") for (int m = 0; m < 4; ++m) _Pragma("unroll") for (int n = 0; n < 2; ++n) _Pragma("unroll") for (int k = 0; k < 2; ++k) \
;         acc[ai][bj][m][n] = __builtin_amdgcn_mfma_f32_16x16x32_bf16(Bt[n][k], At[m][k], acc[ai][bj][m][n], 0, 0, 0); __builtin_amdgcn_s_setprio(0); } while (0)
; #define PG8_WAIT_V(n) asm volatile("s_waitcnt vmcnt(" #n ")" ::: "memory")
; #define PG8_WAIT_L(n) asm volatile("s_waitcnt lgkmcnt(" #n ")" ::: "memory")
; #define PG8_BAR __builtin_amdgcn_s_barrier()
; #define PG8_SCHED __builtin_amdgcn_sched_barrier(0)
; template <class Epi, class Sched, bool ALIGN_EPI = false, bool SP2 = false>
; __device__ __forceinline__ void gemm_phase(PG8_LAS unsigned char* lds, const Gemm g, const Sched& S, const Epi& E) {
;     ...
;             PG8_WAIT_V(8); PG8_WAIT_L(0); PG8_BAR; PG8_MMA(1, 0, At, B0); PG8_MMA(1, 1, At, B1); PG8_BAR; PG8_SCHED;
;             PG8_LDB(B0, 1, 0); PG8_LDB(B1, 1, 1); PG8_SCHED; PG8_LDA(At, 1, 0); PG8_STAGE(PG8_SA(0, 1), a2 + hstep, voffA);
;             PG8_WAIT_V(8); PG8_WAIT_L(0); PG8_BAR; PG8_MMA(0, 0, At, B0); PG8_MMA(0, 1, At, B1); PG8_BAR; PG8_SCHED;
	s_setprio 1
	s_waitcnt lgkmcnt(0)
	v_mfma_f32_16x16x32_bf16 v[70:73], v[50:53], v[186:189], 0
	v_mfma_f32_16x16x32_bf16 v[62:65], v[162:165], v[186:189], 0
	v_mfma_f32_16x16x32_bf16 v[46:49], v[50:53], v[202:205], 0
	v_mfma_f32_16x16x32_bf16 v[38:41], v[162:165], v[202:205], 0
	v_mfma_f32_16x16x32_bf16 v[30:33], v[50:53], v[222:225], 0
	v_mfma_f32_16x16x32_bf16 v[22:25], v[162:165], v[222:225], 0
	v_mfma_f32_16x16x32_bf16 v[14:17], v[50:53], v[230:233], 0
	v_mfma_f32_16x16x32_bf16 v[6:9], v[162:165], v[230:233], 0
	v_mfma_f32_16x16x32_bf16 v[70:73], v[54:57], v[198:201], v[70:73]
	v_mfma_f32_16x16x32_bf16 v[62:65], v[166:169], v[198:201], v[62:65]
	v_mfma_f32_16x16x32_bf16 v[46:49], v[54:57], v[206:209], v[46:49]
	v_mfma_f32_16x16x32_bf16 v[38:41], v[166:169], v[206:209], v[38:41]
	v_mfma_f32_16x16x32_bf16 v[30:33], v[54:57], v[226:229], v[30:33]
	v_mfma_f32_16x16x32_bf16 v[22:25], v[166:169], v[226:229], v[22:25]
	v_mfma_f32_16x16x32_bf16 v[14:17], v[54:57], v[234:237], v[14:17]
	v_mfma_f32_16x16x32_bf16 v[6:9], v[166:169], v[234:237], v[6:9]
	s_setprio 0
	s_setprio 1
	v_mfma_f32_16x16x32_bf16 v[42:45], v[170:173], v[202:205], 0
	v_mfma_f32_16x16x32_bf16 v[34:37], v[178:181], v[202:205], 0
	v_mfma_f32_16x16x32_bf16 v[26:29], v[170:173], v[222:225], 0
	v_mfma_f32_16x16x32_bf16 v[18:21], v[178:181], v[222:225], 0
	v_mfma_f32_16x16x32_bf16 v[10:13], v[170:173], v[230:233], 0
	v_mfma_f32_16x16x32_bf16 v[2:5], v[178:181], v[230:233], 0
	v_mfma_f32_16x16x32_bf16 v[50:53], v[170:173], v[186:189], 0
	v_mfma_f32_16x16x32_bf16 v[54:57], v[178:181], v[186:189], 0
	v_mfma_f32_16x16x32_bf16 v[42:45], v[174:177], v[206:209], v[42:45]
	v_mfma_f32_16x16x32_bf16 v[34:37], v[182:185], v[206:209], v[34:37]
	v_mfma_f32_16x16x32_bf16 v[26:29], v[174:177], v[226:229], v[26:29]
	v_mfma_f32_16x16x32_bf16 v[18:21], v[182:185], v[226:229], v[18:21]
	v_mfma_f32_16x16x32_bf16 v[10:13], v[174:177], v[234:237], v[10:13]
	v_mfma_f32_16x16x32_bf16 v[2:5], v[182:185], v[234:237], v[2:5]
	v_mfma_f32_16x16x32_bf16 v[50:53], v[174:177], v[198:201], v[50:53]
	v_mfma_f32_16x16x32_bf16 v[54:57], v[182:185], v[198:201], v[54:57]
	s_setprio 0
	s_barrier
	s_add_i32 s65, 0, 0x18000
	v_add_u32_e32 v161, s65, v157
	s_add_i32 s66, 0, 0x1c000
	ds_read_b128 v[58:61], v161
	ds_read_b128 v[66:69], v161 offset:1024
	ds_read_b128 v[162:165], v161 offset:2048
	ds_read_b128 v[166:169], v161 offset:3072
	v_add_u32_e32 v161, s66, v157
	ds_read_b128 v[170:173], v161
	ds_read_b128 v[174:177], v161 offset:1024
	ds_read_b128 v[178:181], v161 offset:2048
	ds_read_b128 v[182:185], v161 offset:3072
	s_add_u32 s30, s50, 0x40000
	s_addc_u32 s31, s51, 0
	s_mov_b32 m0, s54
	v_lshl_add_u64 v[240:241], s[30:31], 0, v[138:139]
	ds_read_b128 v[186:189], v160 offset:32768
	ds_read_b128 v[198:201], v160 offset:33792
	ds_read_b128 v[202:205], v160 offset:34816
	ds_read_b128 v[206:209], v160 offset:35840
	ds_read_b128 v[222:225], v160 offset:36864
	ds_read_b128 v[226:229], v160 offset:37888
	ds_read_b128 v[230:233], v160 offset:38912
	ds_read_b128 v[234:237], v160 offset:39936
	global_load_lds_dwordx4 v[240:241], off
	v_lshl_add_u64 v[240:241], s[30:31], 0, v[142:143]
	s_mov_b32 m0, s55
	s_nop 0
	global_load_lds_dwordx4 v[240:241], off
	s_waitcnt vmcnt(8)
	s_waitcnt lgkmcnt(0)
	s_barrier
	s_setprio 1
	s_waitcnt lgkmcnt(0)
	v_mfma_f32_16x16x32_bf16 v[134:137], v[58:61], v[186:189], v[134:137]
	v_mfma_f32_16x16x32_bf16 v[126:129], v[162:165], v[186:189], v[126:129]
	v_mfma_f32_16x16x32_bf16 v[118:121], v[58:61], v[202:205], v[118:121]
	v_mfma_f32_16x16x32_bf16 v[110:113], v[162:165], v[202:205], v[110:113]
	v_mfma_f32_16x16x32_bf16 v[102:105], v[58:61], v[222:225], v[102:105]
	v_mfma_f32_16x16x32_bf16 v[94:97], v[162:165], v[222:225], v[94:97]
	v_mfma_f32_16x16x32_bf16 v[86:89], v[58:61], v[230:233], v[86:89]
	v_mfma_f32_16x16x32_bf16 v[78:81], v[162:165], v[230:233], v[78:81]
	v_mfma_f32_16x16x32_bf16 v[134:137], v[66:69], v[198:201], v[134:137]
	v_mfma_f32_16x16x32_bf16 v[126:129], v[166:169], v[198:201], v[126:129]
	v_mfma_f32_16x16x32_bf16 v[118:121], v[66:69], v[206:209], v[118:121]
	v_mfma_f32_16x16x32_bf16 v[110:113], v[166:169], v[206:209], v[110:113]
	v_mfma_f32_16x16x32_bf16 v[102:105], v[66:69], v[226:229], v[102:105]
	v_mfma_f32_16x16x32_bf16 v[94:97], v[166:169], v[226:229], v[94:97]
	v_mfma_f32_16x16x32_bf16 v[86:89], v[66:69], v[234:237], v[86:89]
	v_mfma_f32_16x16x32_bf16 v[78:81], v[166:169], v[234:237], v[78:81]
	s_setprio 0
	s_setprio 1
	v_mfma_f32_16x16x32_bf16 v[130:133], v[170:173], v[186:189], v[130:133]
	v_mfma_f32_16x16x32_bf16 v[122:125], v[178:181], v[186:189], v[122:125]
	v_mfma_f32_16x16x32_bf16 v[114:117], v[170:173], v[202:205], v[114:117]
	v_mfma_f32_16x16x32_bf16 v[106:109], v[178:181], v[202:205], v[106:109]
	v_mfma_f32_16x16x32_bf16 v[98:101], v[170:173], v[222:225], v[98:101]
	v_mfma_f32_16x16x32_bf16 v[90:93], v[178:181], v[222:225], v[90:93]
	v_mfma_f32_16x16x32_bf16 v[82:85], v[170:173], v[230:233], v[82:85]
	v_mfma_f32_16x16x32_bf16 v[74:77], v[178:181], v[230:233], v[74:77]
	v_mfma_f32_16x16x32_bf16 v[130:133], v[174:177], v[198:201], v[130:133]
	v_mfma_f32_16x16x32_bf16 v[122:125], v[182:185], v[198:201], v[122:125]
	v_mfma_f32_16x16x32_bf16 v[114:117], v[174:177], v[206:209], v[114:117]
	v_mfma_f32_16x16x32_bf16 v[106:109], v[182:185], v[206:209], v[106:109]
	v_mfma_f32_16x16x32_bf16 v[98:101], v[174:177], v[226:229], v[98:101]
	v_mfma_f32_16x16x32_bf16 v[90:93], v[182:185], v[226:229], v[90:93]
	v_mfma_f32_16x16x32_bf16 v[82:85], v[174:177], v[234:237], v[82:85]
	v_mfma_f32_16x16x32_bf16 v[74:77], v[182:185], v[234:237], v[74:77]
	s_setprio 0
	s_barrier
; #define PG8_STAGE(bufoff, gbase, voff) do { _Pragma("unroll") for (int _i = 0; _i < 2; ++_i) \
;         __builtin_amdgcn_global_load_lds((const unsigned*)((const char*)(gbase) + (voff)[_i]), (PG8_LAS unsigned*)(lds + (bufoff) + ldsw + _i * 8192), 16, 0, 0); } while (0)
; #define PG8_LDA(dst, b, h) do { _Pragma("unroll") for (int m = 0; m < 4; ++m) _Pragma("unroll") for (int k = 0; k < 2; ++k) dst[m][k] = *(const PG8_LAS bf16x8*)(lds + PG8_SA(b, h) + aoff + m * 2048 + k * 1024); } while (0)
; #define PG8_MMA(ai, bj, At, Bt) do { __builtin_amdgcn_s_setprio(1); _Pragma("unroll") for (int m = 0; m < 4; ++m) _Pragma("unroll") for (int n = 0; n < 2; ++n) _Pragma("unroll") for (int k = 0; k < 2; ++k) \
;         acc[ai][bj][m][n] = __builtin_amdgcn_mfma_f32_16x16x32_bf16(Bt[n][k], At[m][k], acc[ai][bj][m][n], 0, 0, 0); __builtin_amdgcn_s_setprio(0); } while (0)
; #define PG8_WAIT_V(n) asm volatile("s_waitcnt vmcnt(" #n ")" ::: "memory")
; #define PG8_WAIT_L(n) asm volatile("s_waitcnt lgkmcnt(" #n ")" ::: "memory")
; #define PG8_BAR __builtin_amdgcn_s_barrier()
; #define PG8_SCHED __builtin_amdgcn_sched_barrier(0)
; template <class Epi, class Sched, bool ALIGN_EPI = false, bool SP2 = false>
; __device__ __forceinline__ void gemm_phase(PG8_LAS unsigned char* lds, const Gemm g, const Sched& S, const Epi& E) {
;     ...
;         for (int t = 0; t < nt; t += 2) {
;             const bool last = (t == nt - 2);
;             const char* a1 = cA + (size_t)(t + 1) * kstep;
;             const char* a2 = last ? nA : cA + (size_t)(t + 2) * kstep; const char* b2 = last ? nB : cB + (size_t)(t + 2) * kstep;
;     ...
;             PG8_LDA(At, 1, 1); PG8_STAGE(PG8_SB(1, 0), b3, voffB); PG8_STAGE(PG8_SB(1, 1), b3 + hstep, voffB); PG8_STAGE(PG8_SA(1, 0), a3, voffA);
;             PG8_WAIT_V(8); PG8_WAIT_L(0); PG8_BAR; PG8_MMA(1, 0, At, B0); PG8_MMA(1, 1, At, B1); PG8_BAR; PG8_SCHED;
	s_add_i32 s30, s65, s33
	v_lshl_add_u64 v[152:153], v[152:153], 0, s[0:1]
	s_mov_b32 m0, s30
	ds_read_b128 v[186:189], v160 offset:49152
	ds_read_b128 v[198:201], v160 offset:50176
	ds_read_b128 v[202:205], v160 offset:51200
	ds_read_b128 v[206:209], v160 offset:52224
	ds_read_b128 v[222:225], v160 offset:53248
	ds_read_b128 v[226:229], v160 offset:54272
	ds_read_b128 v[230:233], v160 offset:55296
	ds_read_b128 v[234:237], v160 offset:56320
	global_load_lds_dwordx4 v[152:153], off
	s_add_i32 m0, s30, 0x2000
	s_add_u32 s30, s48, 0x40080
	v_lshl_add_u64 v[152:153], v[190:191], 0, s[0:1]
	s_addc_u32 s31, s49, 0
	s_add_i32 s48, s66, s33
	global_load_lds_dwordx4 v[152:153], off
	v_lshl_add_u64 v[152:153], s[30:31], 0, v[140:141]
	s_mov_b32 m0, s48
	s_nop 0
	global_load_lds_dwordx4 v[152:153], off
	v_lshl_add_u64 v[152:153], s[30:31], 0, v[144:145]
	s_add_i32 m0, s48, 0x2000
	s_nop 0
	global_load_lds_dwordx4 v[152:153], off
	v_lshl_add_u64 v[152:153], v[210:211], 0, s[0:1]
	s_mov_b32 m0, s56
	s_nop 0
	global_load_lds_dwordx4 v[152:153], off
	v_lshl_add_u64 v[152:153], v[238:239], 0, s[0:1]
	s_mov_b32 m0, s57
	s_nop 0
	global_load_lds_dwordx4 v[152:153], off
	s_waitcnt vmcnt(8)
	s_waitcnt lgkmcnt(0)
	s_barrier
	s_setprio 1
	s_waitcnt lgkmcnt(0)
	v_mfma_f32_16x16x32_bf16 v[70:73], v[58:61], v[186:189], v[70:73]
	v_mfma_f32_16x16x32_bf16 v[62:65], v[162:165], v[186:189], v[62:65]
	v_mfma_f32_16x16x32_bf16 v[46:49], v[58:61], v[202:205], v[46:49]
	v_mfma_f32_16x16x32_bf16 v[38:41], v[162:165], v[202:205], v[38:41]
	v_mfma_f32_16x16x32_bf16 v[30:33], v[58:61], v[222:225], v[30:33]
	v_mfma_f32_16x16x32_bf16 v[22:25], v[162:165], v[222:225], v[22:25]
	v_mfma_f32_16x16x32_bf16 v[14:17], v[58:61], v[230:233], v[14:17]
	v_mfma_f32_16x16x32_bf16 v[6:9], v[162:165], v[230:233], v[6:9]
	v_mfma_f32_16x16x32_bf16 v[70:73], v[66:69], v[198:201], v[70:73]
	v_mfma_f32_16x16x32_bf16 v[62:65], v[166:169], v[198:201], v[62:65]
	v_mfma_f32_16x16x32_bf16 v[46:49], v[66:69], v[206:209], v[46:49]
	v_mfma_f32_16x16x32_bf16 v[38:41], v[166:169], v[206:209], v[38:41]
	v_mfma_f32_16x16x32_bf16 v[30:33], v[66:69], v[226:229], v[30:33]
	v_mfma_f32_16x16x32_bf16 v[22:25], v[166:169], v[226:229], v[22:25]
	v_mfma_f32_16x16x32_bf16 v[14:17], v[66:69], v[234:237], v[14:17]
	v_mfma_f32_16x16x32_bf16 v[6:9], v[166:169], v[234:237], v[6:9]
	s_setprio 0
	s_setprio 1
	v_mfma_f32_16x16x32_bf16 v[50:53], v[170:173], v[186:189], v[50:53]
	v_mfma_f32_16x16x32_bf16 v[66:69], v[174:177], v[198:201], v[50:53]
	v_mfma_f32_16x16x32_bf16 v[50:53], v[178:181], v[186:189], v[54:57]
	v_mfma_f32_16x16x32_bf16 v[42:45], v[170:173], v[202:205], v[42:45]
	v_mfma_f32_16x16x32_bf16 v[34:37], v[178:181], v[202:205], v[34:37]
	v_mfma_f32_16x16x32_bf16 v[26:29], v[170:173], v[222:225], v[26:29]
	v_mfma_f32_16x16x32_bf16 v[18:21], v[178:181], v[222:225], v[18:21]
	v_mfma_f32_16x16x32_bf16 v[10:13], v[170:173], v[230:233], v[10:13]
	v_mfma_f32_16x16x32_bf16 v[2:5], v[178:181], v[230:233], v[2:5]
	v_mfma_f32_16x16x32_bf16 v[58:61], v[182:185], v[198:201], v[50:53]
	v_mfma_f32_16x16x32_bf16 v[42:45], v[174:177], v[206:209], v[42:45]
	v_mfma_f32_16x16x32_bf16 v[34:37], v[182:185], v[206:209], v[34:37]
	v_mfma_f32_16x16x32_bf16 v[26:29], v[174:177], v[226:229], v[26:29]
	v_mfma_f32_16x16x32_bf16 v[18:21], v[182:185], v[226:229], v[18:21]
	v_mfma_f32_16x16x32_bf16 v[10:13], v[174:177], v[234:237], v[10:13]
	v_mfma_f32_16x16x32_bf16 v[2:5], v[182:185], v[234:237], v[2:5]
	s_setprio 0
	s_barrier
	s_add_i32 s64, s64, 2
	s_add_u32 s46, s46, 0x100
	s_addc_u32 s47, s47, 0
	s_add_u32 s62, s62, 0x100
	s_addc_u32 s63, s63, 0
	s_cmp_gt_u32 s64, 13
	s_cbranch_scc0 .LBB0_781
	s_branch .Lpeel_exit_p4

; #define PG8_STAGE(bufoff, gbase, voff) do { _Pragma("unroll") for (int _i = 0; _i < 2; ++_i) \
;         __builtin_amdgcn_global_load_lds((const unsigned*)((const char*)(gbase) + (voff)[_i]), (PG8_LAS unsigned*)(lds + (bufoff) + ldsw + _i * 8192), 16, 0, 0); } while (0)
; #define PG8_WAIT_V(n) asm volatile("s_waitcnt vmcnt(" #n ")" ::: "memory")
; #define PG8_BAR __builtin_amdgcn_s_barrier()
; template <class Epi, class Sched, bool ALIGN_EPI = false, bool SP2 = false>
; __device__ __forceinline__ void gemm_phase(PG8_LAS unsigned char* lds, const Gemm g, const Sched& S, const Epi& E) {
;     ...
;     for (int i = 0; i < 2; ++i) { int R, C; stage_rc(tid * 16 + i * 8192, R, C); const int Rb = Epi::PERM ? ((R & ~31) + perm32(R & 31)) : R;
;         voffA[i] = (unsigned)(R * K + C) * 2u; voffB[i] = (unsigned)(Rb * K + C) * 2u; }
;     const size_t kstep = (size_t)(BK * 2);
;     const size_t hstep = (size_t)HALF * K * 2;
;     const size_t tstep = 2 * hstep;
;     const unsigned ldsw = (unsigned)wid * 1024u;
;     const int aoff = lds_byte(wr * 64 + fr, fq * 8), boff = lds_byte(wc * 32 + fr, fq * 8);
;     ...
;         PG8_STAGE(PG8_SB(0, 0), cB, voffB); PG8_STAGE(PG8_SB(0, 1), cB + hstep, voffB); PG8_STAGE(PG8_SA(0, 0), cA, voffA); PG8_STAGE(PG8_SA(0, 1), cA + hstep, voffA);
;         if (wr == 1) PG8_BAR;
;         PG8_WAIT_V(2); PG8_BAR;
;         PG8_STAGE(PG8_SB(1, 0), cB + kstep, voffB); PG8_STAGE(PG8_SA(1, 0), cA + kstep, voffA); PG8_STAGE(PG8_SB(1, 1), cB + hstep + kstep, voffB);
;         PG8_WAIT_V(6); PG8_BAR;
.LBB0_854:
	v_bfe_u32 v20, v10, 4, 2
	v_and_b32_e32 v190, 15, v10
	v_lshlrev_b32_e32 v11, 4, v20
	v_lshlrev_b32_e32 v10, 2, v10
	s_and_b32 s52, s9, 3
	s_lshl_b32 s53, s8, 6
	v_lshl_or_b32 v11, v190, 6, v11
	s_lshl_b32 s8, s8, 13
	v_and_b32_e32 v10, 32, v10
	v_lshl_add_u64 v[12:13], s[44:45], 0, v[0:1]
	v_mov_b32_e32 v159, v1
	v_readlane_b32 s20, v254, 54
	v_bitop3_b32 v22, v11, s8, v10 bitop3:0xde
	s_lshl_b32 s8, s52, 12
	v_lshl_add_u64 v[14:15], s[44:45], 0, v[158:159]
	v_mov_b32_e32 v163, v1
	v_readlane_b32 s21, v254, 55
	v_bitop3_b32 v191, v11, s8, v10 bitop3:0xde
	s_add_i32 m0, s48, 0x18000
	v_lshl_add_u64 v[10:11], v[12:13], 0, s[0:1]
	v_lshl_add_u64 v[16:17], s[20:21], 0, v[162:163]
	v_mov_b32_e32 v161, v1
	s_waitcnt vmcnt(2)
	s_barrier
	global_load_lds_dwordx4 v[10:11], off
	v_lshl_add_u64 v[10:11], v[14:15], 0, s[0:1]
	s_add_i32 m0, s48, 0x1a000
	s_add_i32 s54, s48, 0x8000
	s_add_i32 s55, s48, 0xa000
	v_lshl_add_u64 v[18:19], s[20:21], 0, v[160:161]
	global_load_lds_dwordx4 v[10:11], off
	v_lshl_add_u64 v[10:11], v[16:17], 0, s[0:1]
	s_mov_b32 m0, s54
	s_add_u32 s8, s44, 0xb0080
	global_load_lds_dwordx4 v[10:11], off
	v_lshl_add_u64 v[10:11], v[18:19], 0, s[0:1]
	s_mov_b32 m0, s55
	s_addc_u32 s9, s45, 0
	global_load_lds_dwordx4 v[10:11], off
	s_add_i32 m0, s48, 0x1c000
	v_lshl_add_u64 v[10:11], s[8:9], 0, v[0:1]
	global_load_lds_dwordx4 v[10:11], off
	v_lshl_add_u64 v[10:11], s[8:9], 0, v[158:159]
	s_add_i32 m0, s48, 0x1e000
	s_cmpk_lt_u32 s6, 0x100
	global_load_lds_dwordx4 v[10:11], off
	s_movk_i32 s6, 0xb00
	v_lshrrev_b32_e32 v7, 1, v7
	v_mul_lo_u32 v6, v6, s6
	s_mov_b32 s14, 0xb000
	v_mad_u64_u32 v[6:7], s[10:11], v7, s14, v[6:7]
	v_or_b32_e32 v6, v6, v8
	v_add_lshl_u32 v6, v6, v9, 1
	v_mov_b32_e32 v7, v1
	s_mov_b64 s[30:31], 0xb0080
	v_lshl_add_u64 v[164:165], v[6:7], 0, s[30:31]
	v_lshrrev_b32_e32 v6, 1, v2
	v_mul_lo_u32 v2, v3, s6
	v_mad_u64_u32 v[2:3], s[10:11], v6, s14, v[2:3]
	s_waitcnt vmcnt(0)
	v_or_b32_e32 v2, v2, v4
	v_lshlrev_b32_e32 v21, 3, v20
	v_add_lshl_u32 v2, v2, v5, 1
	v_mov_b32_e32 v3, v1
	v_readlane_b32 s10, v254, 52
	s_cselect_b64 s[8:9], -1, 0
	v_lshl_or_b32 v193, s52, 6, v21
	s_mov_b32 s56, 0
	v_cmp_eq_u32_e64 s[38:39], 0, v20
	v_lshl_add_u64 v[166:167], v[2:3], 0, s[30:31]
	v_add_u32_e32 v202, 0, v22
	v_readlane_b32 s6, v254, 26
	s_mov_b32 s27, s10
	s_barrier
	v_readlane_b32 s11, v254, 53
	s_branch .LBB0_857

; #define PG8_STAGE(bufoff, gbase, voff) do { _Pragma("unroll") for (int _i = 0; _i < 2; ++_i) \
;         __builtin_amdgcn_global_load_lds((const unsigned*)((const char*)(gbase) + (voff)[_i]), (PG8_LAS unsigned*)(lds + (bufoff) + ldsw + _i * 8192), 16, 0, 0); } while (0)
; #define PG8_LDA(dst, b, h) do { _Pragma("unroll") for (int m = 0; m < 4; ++m) _Pragma("unroll") for (int k = 0; k < 2; ++k) dst[m][k] = *(const PG8_LAS bf16x8*)(lds + PG8_SA(b, h) + aoff + m * 2048 + k * 1024); } while (0)
; #define PG8_LDB(dst, b, h) do { _Pragma("unroll") for (int n = 0; n < 2; ++n) _Pragma("unroll") for (int k = 0; k < 2; ++k) dst[n][k] = *(const PG8_LAS bf16x8*)(lds + PG8_SB(b, h) + boff + n * 2048 + k * 1024); } while (0)
; #define PG8_MMA(ai, bj, At, Bt) do { __builtin_amdgcn_s_setprio(1); _Pragma("unroll") for (int m = 0; m < 4; ++m) _Pragma("unroll") for (int n = 0; n < 2; ++n) _Pragma("unroll") for (int k = 0; k < 2; ++k) \
;         acc[ai][bj][m][n] = __builtin_amdgcn_mfma_f32_16x16x32_bf16(Bt[n][k], At[m][k], acc[ai][bj][m][n], 0, 0, 0); __builtin_amdgcn_s_setprio(0); } while (0)
; #define PG8_WAIT_V(n) asm volatile("s_waitcnt vmcnt(" #n ")" ::: "memory")
; #define PG8_WAIT_L(n) asm volatile("s_waitcnt lgkmcnt(" #n ")" ::: "memory")
; template <class Epi, class Sched, bool ALIGN_EPI = false, bool SP2 = false>
; __device__ __forceinline__ void gemm_phase(PG8_LAS unsigned char* lds, const Gemm g, const Sched& S, const Epi& E) {
;     ...
;             const bool last = (t == nt - 2);
;             const char* a1 = cA + (size_t)(t + 1) * kstep;
;             const char* a2 = last ? nA : cA + (size_t)(t + 2) * kstep; const char* b2 = last ? nB : cB + (size_t)(t + 2) * kstep;
;             const char* a3 = a2 + kstep; const char* b3 = b2 + kstep;
;             if (last && has_next) S.a_ready(nxt);
;             if constexpr (SP2) {
;             PG8_LDB(B0, 0, 0); PG8_LDB(B1, 0, 1); PG8_SCHED; PG8_LDA(At, 0, 0); PG8_STAGE(PG8_SA(1, 1), a1 + hstep, voffA);
;             PG8_WAIT_V(8); PG8_WAIT_L(0); PG8_BAR; PG8_MMA(0, 0, At, B0); PG8_MMA(0, 1, At, B1); PG8_BAR; PG8_SCHED;
;             PG8_LDA(At, 0, 1); PG8_STAGE(PG8_SB(0, 0), b2, voffB); PG8_STAGE(PG8_SB(0, 1), b2 + hstep, voffB); PG8_STAGE(PG8_SA(0, 0), a2, voffA);
;             PG8_WAIT_V(8); PG8_WAIT_L(0); PG8_BAR; PG8_MMA(1, 0, At, B0); PG8_MMA(1, 1, At, B1); PG8_BAR; PG8_SCHED;
.Lpeel_p5:
	s_add_u32 s42, s20, 0x100
	s_addc_u32 s43, s21, 0
	s_add_i32 s30, 0, 0x10000
	s_cmp_eq_u32 s59, 40
	s_cselect_b32 s47, s11, s43
	s_cselect_b32 s46, s10, s42
	s_cselect_b32 s45, s15, s35
	s_cselect_b32 s44, s14, s34
	s_add_i32 s31, 0, 0x14000
	v_add_u32_e32 v134, s30, v191
	v_add_u32_e32 v168, s31, v191
	ds_read_b128 v[114:117], v134
	ds_read_b128 v[126:129], v134 offset:1024
	ds_read_b128 v[130:133], v134 offset:2048
	ds_read_b128 v[134:137], v134 offset:3072
	ds_read_b128 v[146:149], v168
	ds_read_b128 v[150:153], v168 offset:1024
	ds_read_b128 v[154:157], v168 offset:2048
	ds_read_b128 v[168:171], v168 offset:3072
	v_lshl_add_u64 v[188:189], s[20:21], 0, v[164:165]
	s_add_i32 m0, s48, 0xc000
	ds_read_b128 v[172:175], v202
	ds_read_b128 v[176:179], v202 offset:1024
	ds_read_b128 v[180:183], v202 offset:2048
	ds_read_b128 v[184:187], v202 offset:3072
	ds_read_b128 v[198:201], v202 offset:4096
	ds_read_b128 v[204:207], v202 offset:5120
	ds_read_b128 v[208:211], v202 offset:6144
	ds_read_b128 v[222:225], v202 offset:7168
	global_load_lds_dwordx4 v[188:189], off
	v_lshl_add_u64 v[188:189], s[20:21], 0, v[166:167]
	s_add_i32 m0, s48, 0xe000
	s_nop 0
	global_load_lds_dwordx4 v[188:189], off
	s_waitcnt vmcnt(63)
	s_waitcnt lgkmcnt(0)
	s_barrier
	s_setprio 1
	s_waitcnt lgkmcnt(0)
	v_mfma_f32_16x16x32_bf16 v[142:145], v[114:117], v[172:175], 0
	v_mfma_f32_16x16x32_bf16 v[138:141], v[130:133], v[172:175], 0
	v_mfma_f32_16x16x32_bf16 v[110:113], v[114:117], v[180:183], 0
	v_mfma_f32_16x16x32_bf16 v[106:109], v[130:133], v[180:183], 0
	v_mfma_f32_16x16x32_bf16 v[94:97], v[114:117], v[198:201], 0
	v_mfma_f32_16x16x32_bf16 v[90:93], v[130:133], v[198:201], 0
	v_mfma_f32_16x16x32_bf16 v[78:81], v[114:117], v[208:211], 0
	v_mfma_f32_16x16x32_bf16 v[74:77], v[130:133], v[208:211], 0
	v_mfma_f32_16x16x32_bf16 v[142:145], v[126:129], v[176:179], v[142:145]
	v_mfma_f32_16x16x32_bf16 v[138:141], v[134:137], v[176:179], v[138:141]
	v_mfma_f32_16x16x32_bf16 v[110:113], v[126:129], v[184:187], v[110:113]
	v_mfma_f32_16x16x32_bf16 v[106:109], v[134:137], v[184:187], v[106:109]
	v_mfma_f32_16x16x32_bf16 v[94:97], v[126:129], v[204:207], v[94:97]
	v_mfma_f32_16x16x32_bf16 v[90:93], v[134:137], v[204:207], v[90:93]
	v_mfma_f32_16x16x32_bf16 v[78:81], v[126:129], v[222:225], v[78:81]
	v_mfma_f32_16x16x32_bf16 v[74:77], v[134:137], v[222:225], v[74:77]
	s_setprio 0
	s_setprio 1
	v_mfma_f32_16x16x32_bf16 v[122:125], v[146:149], v[172:175], 0
	v_mfma_f32_16x16x32_bf16 v[118:121], v[154:157], v[172:175], 0
	v_mfma_f32_16x16x32_bf16 v[102:105], v[146:149], v[180:183], 0
	v_mfma_f32_16x16x32_bf16 v[98:101], v[154:157], v[180:183], 0
	v_mfma_f32_16x16x32_bf16 v[86:89], v[146:149], v[198:201], 0
	v_mfma_f32_16x16x32_bf16 v[82:85], v[154:157], v[198:201], 0
	v_mfma_f32_16x16x32_bf16 v[70:73], v[146:149], v[208:211], 0
	v_mfma_f32_16x16x32_bf16 v[66:69], v[154:157], v[208:211], 0
	v_mfma_f32_16x16x32_bf16 v[122:125], v[150:153], v[176:179], v[122:125]
	v_mfma_f32_16x16x32_bf16 v[118:121], v[168:171], v[176:179], v[118:121]
	v_mfma_f32_16x16x32_bf16 v[102:105], v[150:153], v[184:187], v[102:105]
	v_mfma_f32_16x16x32_bf16 v[98:101], v[168:171], v[184:187], v[98:101]
	v_mfma_f32_16x16x32_bf16 v[86:89], v[150:153], v[204:207], v[86:89]
	v_mfma_f32_16x16x32_bf16 v[82:85], v[168:171], v[204:207], v[82:85]
	v_mfma_f32_16x16x32_bf16 v[70:73], v[150:153], v[222:225], v[70:73]
	v_mfma_f32_16x16x32_bf16 v[66:69], v[168:171], v[222:225], v[66:69]
	s_setprio 0
	s_barrier
	s_add_i32 s20, s30, s33
	v_lshl_add_u64 v[188:189], s[44:45], 0, v[0:1]
	s_mov_b32 m0, s20
	ds_read_b128 v[172:175], v202 offset:16384
	ds_read_b128 v[176:179], v202 offset:17408
	ds_read_b128 v[180:183], v202 offset:18432
	ds_read_b128 v[184:187], v202 offset:19456
	ds_read_b128 v[198:201], v202 offset:20480
	ds_read_b128 v[204:207], v202 offset:21504
	ds_read_b128 v[208:211], v202 offset:22528
	ds_read_b128 v[222:225], v202 offset:23552
	global_load_lds_dwordx4 v[188:189], off
	s_add_i32 m0, s20, 0x2000
	s_add_u32 s20, s44, 0xb0000
	v_lshl_add_u64 v[226:227], s[44:45], 0, v[158:159]
	s_addc_u32 s21, s45, 0
	s_add_i32 s30, s31, s33
	global_load_lds_dwordx4 v[226:227], off
	v_lshl_add_u64 v[228:229], s[20:21], 0, v[0:1]
	s_mov_b32 m0, s30
	v_lshl_add_u64 v[230:231], s[46:47], 0, v[160:161]
	global_load_lds_dwordx4 v[228:229], off
	v_lshl_add_u64 v[228:229], s[20:21], 0, v[158:159]
	s_add_i32 m0, s30, 0x2000
	s_nop 0
	global_load_lds_dwordx4 v[228:229], off
	v_lshl_add_u64 v[228:229], s[46:47], 0, v[162:163]
	s_mov_b32 m0, s48
	s_nop 0
	global_load_lds_dwordx4 v[228:229], off
	s_mov_b32 m0, s49
	s_nop 0
	global_load_lds_dwordx4 v[230:231], off
	s_waitcnt vmcnt(63)
	s_waitcnt lgkmcnt(0)
	s_barrier
; #define PG8_STAGE(bufoff, gbase, voff) do { _Pragma("unroll") for (int _i = 0; _i < 2; ++_i) \
;         __builtin_amdgcn_global_load_lds((const unsigned*)((const char*)(gbase) + (voff)[_i]), (PG8_LAS unsigned*)(lds + (bufoff) + ldsw + _i * 8192), 16, 0, 0); } while (0)
; #define PG8_LDA(dst, b, h) do { _Pragma("unroll") for (int m = 0; m < 4; ++m) _Pragma("unroll") for (int k = 0; k < 2; ++k) dst[m][k] = *(const PG8_LAS bf16x8*)(lds + PG8_SA(b, h) + aoff + m * 2048 + k * 1024); } while (0)
; #define PG8_LDB(dst, b, h) do { _Pragma("unroll") for (int n = 0; n < 2; ++n) _Pragma("unroll") for (int k = 0; k < 2; ++k) dst[n][k] = *(const PG8_LAS bf16x8*)(lds + PG8_SB(b, h) + boff + n * 2048 + k * 1024); } while (0)
; #define PG8_MMA(ai, bj, At, Bt) do { __builtin_amdgcn_s_setprio(1); _Pragma("unroll") for (int m = 0; m < 4; ++m) _Pragma("unroll") for (int n = 0; n < 2; ++n) _Pragma("unroll") for (int k = 0; k < 2; ++k) \
;         acc[ai][bj][m][n] = __builtin_amdgcn_mfma_f32_16x16x32_bf16(Bt[n][k], At[m][k], acc[ai][bj][m][n], 0, 0, 0); __builtin_amdgcn_s_setprio(0); } while (0)
; #define PG8_WAIT_V(n) asm volatile("s_waitcnt vmcnt(" #n ")" ::: "memory")
; #define PG8_WAIT_L(n) asm volatile("s_waitcnt lgkmcnt(" #n ")" ::: "memory")
; #define PG8_BAR __builtin_amdgcn_s_barrier()
; #define PG8_SCHED __builtin_amdgcn_sched_barrier(0)
; template <class Epi, class Sched, bool ALIGN_EPI = false, bool SP2 = false>
; __device__ __forceinline__ void gemm_phase(PG8_LAS unsigned char* lds, const Gemm g, const Sched& S, const Epi& E) {
;     ...
;             PG8_WAIT_V(8); PG8_WAIT_L(0); PG8_BAR; PG8_MMA(1, 0, At, B0); PG8_MMA(1, 1, At, B1); PG8_BAR; PG8_SCHED;
;             PG8_LDB(B0, 1, 0); PG8_LDB(B1, 1, 1); PG8_SCHED; PG8_LDA(At, 1, 0); PG8_STAGE(PG8_SA(0, 1), a2 + hstep, voffA);
;             PG8_WAIT_V(8); PG8_WAIT_L(0); PG8_BAR; PG8_MMA(0, 0, At, B0); PG8_MMA(0, 1, At, B1); PG8_BAR; PG8_SCHED;
	s_setprio 1
	s_waitcnt lgkmcnt(0)
	v_mfma_f32_16x16x32_bf16 v[62:65], v[114:117], v[172:175], 0
	v_mfma_f32_16x16x32_bf16 v[58:61], v[130:133], v[172:175], 0
	v_mfma_f32_16x16x32_bf16 v[46:49], v[114:117], v[180:183], 0
	v_mfma_f32_16x16x32_bf16 v[42:45], v[130:133], v[180:183], 0
	v_mfma_f32_16x16x32_bf16 v[30:33], v[114:117], v[198:201], 0
	v_mfma_f32_16x16x32_bf16 v[26:29], v[130:133], v[198:201], 0
	v_mfma_f32_16x16x32_bf16 v[14:17], v[114:117], v[208:211], 0
	v_mfma_f32_16x16x32_bf16 v[10:13], v[130:133], v[208:211], 0
	v_mfma_f32_16x16x32_bf16 v[62:65], v[126:129], v[176:179], v[62:65]
	v_mfma_f32_16x16x32_bf16 v[58:61], v[134:137], v[176:179], v[58:61]
	v_mfma_f32_16x16x32_bf16 v[46:49], v[126:129], v[184:187], v[46:49]
	v_mfma_f32_16x16x32_bf16 v[42:45], v[134:137], v[184:187], v[42:45]
	v_mfma_f32_16x16x32_bf16 v[30:33], v[126:129], v[204:207], v[30:33]
	v_mfma_f32_16x16x32_bf16 v[26:29], v[134:137], v[204:207], v[26:29]
	v_mfma_f32_16x16x32_bf16 v[14:17], v[126:129], v[222:225], v[14:17]
	v_mfma_f32_16x16x32_bf16 v[10:13], v[134:137], v[222:225], v[10:13]
	s_setprio 0
	s_setprio 1
	v_mfma_f32_16x16x32_bf16 v[54:57], v[146:149], v[172:175], 0
	v_mfma_f32_16x16x32_bf16 v[50:53], v[154:157], v[172:175], 0
	v_mfma_f32_16x16x32_bf16 v[38:41], v[146:149], v[180:183], 0
	v_mfma_f32_16x16x32_bf16 v[34:37], v[154:157], v[180:183], 0
	v_mfma_f32_16x16x32_bf16 v[22:25], v[146:149], v[198:201], 0
	v_mfma_f32_16x16x32_bf16 v[18:21], v[154:157], v[198:201], 0
	v_mfma_f32_16x16x32_bf16 v[6:9], v[146:149], v[208:211], 0
	v_mfma_f32_16x16x32_bf16 v[2:5], v[154:157], v[208:211], 0
	v_mfma_f32_16x16x32_bf16 v[54:57], v[150:153], v[176:179], v[54:57]
	v_mfma_f32_16x16x32_bf16 v[50:53], v[168:171], v[176:179], v[50:53]
	v_mfma_f32_16x16x32_bf16 v[38:41], v[150:153], v[184:187], v[38:41]
	v_mfma_f32_16x16x32_bf16 v[34:37], v[168:171], v[184:187], v[34:37]
	v_mfma_f32_16x16x32_bf16 v[22:25], v[150:153], v[204:207], v[22:25]
	v_mfma_f32_16x16x32_bf16 v[18:21], v[168:171], v[204:207], v[18:21]
	v_mfma_f32_16x16x32_bf16 v[6:9], v[150:153], v[222:225], v[6:9]
	v_mfma_f32_16x16x32_bf16 v[2:5], v[168:171], v[222:225], v[2:5]
	s_setprio 0
	s_barrier
	s_add_i32 s30, 0, 0x18000
	s_add_i32 s31, 0, 0x1c000
	v_add_u32_e32 v134, s30, v191
	v_add_u32_e32 v168, s31, v191
	ds_read_b128 v[114:117], v134
	ds_read_b128 v[126:129], v134 offset:1024
	ds_read_b128 v[130:133], v134 offset:2048
	ds_read_b128 v[134:137], v134 offset:3072
	ds_read_b128 v[146:149], v168
	ds_read_b128 v[150:153], v168 offset:1024
	ds_read_b128 v[154:157], v168 offset:2048
	ds_read_b128 v[168:171], v168 offset:3072
	s_add_u32 s20, s46, 0xb0000
	s_addc_u32 s21, s47, 0
	s_mov_b32 m0, s50
	v_lshl_add_u64 v[232:233], s[20:21], 0, v[162:163]
	ds_read_b128 v[172:175], v202 offset:32768
	ds_read_b128 v[176:179], v202 offset:33792
	ds_read_b128 v[180:183], v202 offset:34816
	ds_read_b128 v[184:187], v202 offset:35840
	ds_read_b128 v[198:201], v202 offset:36864
	ds_read_b128 v[204:207], v202 offset:37888
	ds_read_b128 v[208:211], v202 offset:38912
	ds_read_b128 v[222:225], v202 offset:39936
	global_load_lds_dwordx4 v[232:233], off
	v_lshl_add_u64 v[232:233], s[20:21], 0, v[160:161]
	s_mov_b32 m0, s51
	s_nop 0
	global_load_lds_dwordx4 v[232:233], off
	s_waitcnt vmcnt(8)
	s_waitcnt lgkmcnt(0)
	s_barrier
	s_setprio 1
	s_waitcnt lgkmcnt(0)
	v_mfma_f32_16x16x32_bf16 v[142:145], v[114:117], v[172:175], v[142:145]
	v_mfma_f32_16x16x32_bf16 v[138:141], v[130:133], v[172:175], v[138:141]
	v_mfma_f32_16x16x32_bf16 v[110:113], v[114:117], v[180:183], v[110:113]
	v_mfma_f32_16x16x32_bf16 v[106:109], v[130:133], v[180:183], v[106:109]
	v_mfma_f32_16x16x32_bf16 v[94:97], v[114:117], v[198:201], v[94:97]
	v_mfma_f32_16x16x32_bf16 v[90:93], v[130:133], v[198:201], v[90:93]
	v_mfma_f32_16x16x32_bf16 v[78:81], v[114:117], v[208:211], v[78:81]
	v_mfma_f32_16x16x32_bf16 v[74:77], v[130:133], v[208:211], v[74:77]
	v_mfma_f32_16x16x32_bf16 v[142:145], v[126:129], v[176:179], v[142:145]
	v_mfma_f32_16x16x32_bf16 v[138:141], v[134:137], v[176:179], v[138:141]
	v_mfma_f32_16x16x32_bf16 v[110:113], v[126:129], v[184:187], v[110:113]
	v_mfma_f32_16x16x32_bf16 v[106:109], v[134:137], v[184:187], v[106:109]
	v_mfma_f32_16x16x32_bf16 v[94:97], v[126:129], v[204:207], v[94:97]
	v_mfma_f32_16x16x32_bf16 v[90:93], v[134:137], v[204:207], v[90:93]
	v_mfma_f32_16x16x32_bf16 v[78:81], v[126:129], v[222:225], v[78:81]
	v_mfma_f32_16x16x32_bf16 v[74:77], v[134:137], v[222:225], v[74:77]
	s_setprio 0
	s_setprio 1
	v_mfma_f32_16x16x32_bf16 v[122:125], v[146:149], v[172:175], v[122:125]
	v_mfma_f32_16x16x32_bf16 v[118:121], v[154:157], v[172:175], v[118:121]
	v_mfma_f32_16x16x32_bf16 v[102:105], v[146:149], v[180:183], v[102:105]
	v_mfma_f32_16x16x32_bf16 v[98:101], v[154:157], v[180:183], v[98:101]
	v_mfma_f32_16x16x32_bf16 v[86:89], v[146:149], v[198:201], v[86:89]
	v_mfma_f32_16x16x32_bf16 v[82:85], v[154:157], v[198:201], v[82:85]
	v_mfma_f32_16x16x32_bf16 v[70:73], v[146:149], v[208:211], v[70:73]
	v_mfma_f32_16x16x32_bf16 v[66:69], v[154:157], v[208:211], v[66:69]
	v_mfma_f32_16x16x32_bf16 v[122:125], v[150:153], v[176:179], v[122:125]
	v_mfma_f32_16x16x32_bf16 v[118:121], v[168:171], v[176:179], v[118:121]
	v_mfma_f32_16x16x32_bf16 v[102:105], v[150:153], v[184:187], v[102:105]
	v_mfma_f32_16x16x32_bf16 v[98:101], v[168:171], v[184:187], v[98:101]
	v_mfma_f32_16x16x32_bf16 v[86:89], v[150:153], v[204:207], v[86:89]
	v_mfma_f32_16x16x32_bf16 v[82:85], v[168:171], v[204:207], v[82:85]
	v_mfma_f32_16x16x32_bf16 v[70:73], v[150:153], v[222:225], v[70:73]
	v_mfma_f32_16x16x32_bf16 v[66:69], v[168:171], v[222:225], v[66:69]
	s_setprio 0
	s_barrier
; #define PG8_STAGE(bufoff, gbase, voff) do { _Pragma("unroll") for (int _i = 0; _i < 2; ++_i) \
;         __builtin_amdgcn_global_load_lds((const unsigned*)((const char*)(gbase) + (voff)[_i]), (PG8_LAS unsigned*)(lds + (bufoff) + ldsw + _i * 8192), 16, 0, 0); } while (0)
; #define PG8_LDA(dst, b, h) do { _Pragma("unroll") for (int m = 0; m < 4; ++m) _Pragma("unroll") for (int k = 0; k < 2; ++k) dst[m][k] = *(const PG8_LAS bf16x8*)(lds + PG8_SA(b, h) + aoff + m * 2048 + k * 1024); } while (0)
; #define PG8_MMA(ai, bj, At, Bt) do { __builtin_amdgcn_s_setprio(1); _Pragma("unroll") for (int m = 0; m < 4; ++m) _Pragma("unroll") for (int n = 0; n < 2; ++n) _Pragma("unroll") for (int k = 0; k < 2; ++k) \
;         acc[ai][bj][m][n] = __builtin_amdgcn_mfma_f32_16x16x32_bf16(Bt[n][k], At[m][k], acc[ai][bj][m][n], 0, 0, 0); __builtin_amdgcn_s_setprio(0); } while (0)
; #define PG8_WAIT_V(n) asm volatile("s_waitcnt vmcnt(" #n ")" ::: "memory")
; #define PG8_WAIT_L(n) asm volatile("s_waitcnt lgkmcnt(" #n ")" ::: "memory")
; #define PG8_BAR __builtin_amdgcn_s_barrier()
; #define PG8_SCHED __builtin_amdgcn_sched_barrier(0)
; template <class Epi, class Sched, bool ALIGN_EPI = false, bool SP2 = false>
; __device__ __forceinline__ void gemm_phase(PG8_LAS unsigned char* lds, const Gemm g, const Sched& S, const Epi& E) {
;     ...
;         for (int t = 0; t < nt; t += 2) {
;             const bool last = (t == nt - 2);
;             const char* a1 = cA + (size_t)(t + 1) * kstep;
;             const char* a2 = last ? nA : cA + (size_t)(t + 2) * kstep; const char* b2 = last ? nB : cB + (size_t)(t + 2) * kstep;
;     ...
;             PG8_LDA(At, 1, 1); PG8_STAGE(PG8_SB(1, 0), b3, voffB); PG8_STAGE(PG8_SB(1, 1), b3 + hstep, voffB); PG8_STAGE(PG8_SA(1, 0), a3, voffA);
;             PG8_WAIT_V(8); PG8_WAIT_L(0); PG8_BAR; PG8_MMA(1, 0, At, B0); PG8_MMA(1, 1, At, B1); PG8_BAR; PG8_SCHED;
	s_add_i32 s20, s30, s33
	v_lshl_add_u64 v[188:189], v[188:189], 0, s[0:1]
	s_mov_b32 m0, s20
	ds_read_b128 v[172:175], v202 offset:49152
	ds_read_b128 v[176:179], v202 offset:50176
	ds_read_b128 v[180:183], v202 offset:51200
	ds_read_b128 v[184:187], v202 offset:52224
	ds_read_b128 v[198:201], v202 offset:53248
	ds_read_b128 v[204:207], v202 offset:54272
	ds_read_b128 v[208:211], v202 offset:55296
	ds_read_b128 v[222:225], v202 offset:56320
	global_load_lds_dwordx4 v[188:189], off
	s_add_i32 m0, s20, 0x2000
	s_add_u32 s20, s44, 0xb0080
	v_lshl_add_u64 v[188:189], v[226:227], 0, s[0:1]
	s_addc_u32 s21, s45, 0
	s_add_i32 s30, s31, s33
	global_load_lds_dwordx4 v[188:189], off
	v_lshl_add_u64 v[188:189], s[20:21], 0, v[0:1]
	s_mov_b32 m0, s30
	s_nop 0
	global_load_lds_dwordx4 v[188:189], off
	v_lshl_add_u64 v[188:189], s[20:21], 0, v[158:159]
	s_add_i32 m0, s30, 0x2000
	s_nop 0
	global_load_lds_dwordx4 v[188:189], off
	v_lshl_add_u64 v[188:189], v[228:229], 0, s[0:1]
	s_mov_b32 m0, s54
	s_nop 0
	global_load_lds_dwordx4 v[188:189], off
	v_lshl_add_u64 v[188:189], v[230:231], 0, s[0:1]
	s_mov_b32 m0, s55
	s_nop 0
	global_load_lds_dwordx4 v[188:189], off
	s_waitcnt vmcnt(8)
	s_waitcnt lgkmcnt(0)
	s_barrier
	s_setprio 1
	s_waitcnt lgkmcnt(0)
	v_mfma_f32_16x16x32_bf16 v[62:65], v[114:117], v[172:175], v[62:65]
	v_mfma_f32_16x16x32_bf16 v[58:61], v[130:133], v[172:175], v[58:61]
	v_mfma_f32_16x16x32_bf16 v[46:49], v[114:117], v[180:183], v[46:49]
	v_mfma_f32_16x16x32_bf16 v[42:45], v[130:133], v[180:183], v[42:45]
	v_mfma_f32_16x16x32_bf16 v[30:33], v[114:117], v[198:201], v[30:33]
	v_mfma_f32_16x16x32_bf16 v[26:29], v[130:133], v[198:201], v[26:29]
	v_mfma_f32_16x16x32_bf16 v[14:17], v[114:117], v[208:211], v[14:17]
	v_mfma_f32_16x16x32_bf16 v[10:13], v[130:133], v[208:211], v[10:13]
	v_mfma_f32_16x16x32_bf16 v[62:65], v[126:129], v[176:179], v[62:65]
	v_mfma_f32_16x16x32_bf16 v[58:61], v[134:137], v[176:179], v[58:61]
	v_mfma_f32_16x16x32_bf16 v[46:49], v[126:129], v[184:187], v[46:49]
	v_mfma_f32_16x16x32_bf16 v[42:45], v[134:137], v[184:187], v[42:45]
	v_mfma_f32_16x16x32_bf16 v[30:33], v[126:129], v[204:207], v[30:33]
	v_mfma_f32_16x16x32_bf16 v[26:29], v[134:137], v[204:207], v[26:29]
	v_mfma_f32_16x16x32_bf16 v[14:17], v[126:129], v[222:225], v[14:17]
	v_mfma_f32_16x16x32_bf16 v[10:13], v[134:137], v[222:225], v[10:13]
	s_setprio 0
	s_setprio 1
	v_mfma_f32_16x16x32_bf16 v[54:57], v[146:149], v[172:175], v[54:57]
	v_mfma_f32_16x16x32_bf16 v[50:53], v[154:157], v[172:175], v[50:53]
	v_mfma_f32_16x16x32_bf16 v[38:41], v[146:149], v[180:183], v[38:41]
	v_mfma_f32_16x16x32_bf16 v[34:37], v[154:157], v[180:183], v[34:37]
	v_mfma_f32_16x16x32_bf16 v[22:25], v[146:149], v[198:201], v[22:25]
	v_mfma_f32_16x16x32_bf16 v[18:21], v[154:157], v[198:201], v[18:21]
	v_mfma_f32_16x16x32_bf16 v[6:9], v[146:149], v[208:211], v[6:9]
	v_mfma_f32_16x16x32_bf16 v[2:5], v[154:157], v[208:211], v[2:5]
	v_mfma_f32_16x16x32_bf16 v[54:57], v[150:153], v[176:179], v[54:57]
	v_mfma_f32_16x16x32_bf16 v[50:53], v[168:171], v[176:179], v[50:53]
	v_mfma_f32_16x16x32_bf16 v[38:41], v[150:153], v[184:187], v[38:41]
	v_mfma_f32_16x16x32_bf16 v[34:37], v[168:171], v[184:187], v[34:37]
	v_mfma_f32_16x16x32_bf16 v[22:25], v[150:153], v[204:207], v[22:25]
	v_mfma_f32_16x16x32_bf16 v[18:21], v[168:171], v[204:207], v[18:21]
	v_mfma_f32_16x16x32_bf16 v[6:9], v[150:153], v[222:225], v[6:9]
	v_mfma_f32_16x16x32_bf16 v[2:5], v[168:171], v[222:225], v[2:5]
	s_setprio 0
	s_barrier
	s_add_i32 s59, s59, 2
	s_add_u32 s34, s34, 0x100
	s_addc_u32 s35, s35, 0
	s_cmp_gt_u32 s59, 41
	s_mov_b64 s[20:21], s[42:43]
	s_cbranch_scc0 .LBB0_868
	s_branch .Lpeel_exit_p5
